# attention row-max: NaN-canonicalising self-max pairs folded into the max (s_nop keeps the wait-state distances), 276 VALU ops fewer in NA + ctx attention
# speedup vs baseline: 1.0210x; 1.0034x over previous
.LBB0_1094:
	s_xor_b64 s[44:45], s[16:17], -1
	s_xor_b64 s[16:17], s[10:11], -1
	s_and_b64 vcc, exec, s[38:39]
	v_mov_b32_e32 v33, 0xf149f2ca
	s_cbranch_vccnz .LBB0_1096
	s_nop 5
	s_nop 1
	v_max_f32_e32 v33, v50, v51
	s_nop 1
	v_max_f32_e32 v66, v52, v53
	v_max3_f32 v33, v33, s23, v66
.LBB0_1096:
	s_nop 1
	v_max_f32_e32 v66, v34, v35
	s_nop 1
	v_max_f32_e32 v67, v36, v37
	s_and_b64 vcc, exec, s[38:39]
	v_max3_f32 v33, v33, v66, v67
	s_cbranch_vccnz .LBB0_1100
	s_nop 1
	v_max_f32_e32 v66, v54, v55
	s_nop 1
	v_max_f32_e32 v67, v56, v57
	v_max3_f32 v33, v33, v66, v67
	v_cndmask_b32_e64 v66, 0, 1, s[10:11]
	v_cmp_ne_u32_e64 s[40:41], 1, v66
	s_andn2_b64 vcc, exec, s[10:11]
	s_cbranch_vccz .LBB0_1101

.LBB0_1099:
	s_nop 1
	v_max_f32_e32 v66, v58, v59
	s_nop 1
	v_max_f32_e32 v67, v60, v61
	v_max3_f32 v33, v33, v66, v67
	s_and_b64 vcc, exec, s[40:41]
	s_cbranch_vccz .LBB0_1103
	s_branch .LBB0_1104

.LBB0_1101:
	s_nop 1
	v_max_f32_e32 v66, v38, v39
	s_nop 1
	v_max_f32_e32 v67, v40, v41
	v_max3_f32 v33, v33, v66, v67
	s_and_b64 vcc, exec, s[38:39]
	s_cbranch_vccz .LBB0_1099

.LBB0_1103:
	s_nop 1
	v_max_f32_e32 v66, v42, v43
	s_nop 1
	v_max_f32_e32 v67, v44, v45
	v_max3_f32 v33, v33, v66, v67
.LBB0_1104:
	s_nop 1
	v_max_f32_e32 v66, v62, v63
	s_nop 1
	v_max_f32_e32 v67, v64, v65
	s_and_b64 vcc, exec, s[40:41]
	v_max3_f32 v33, v33, v66, v67
	s_cbranch_vccnz .LBB0_1106
	s_nop 1
	v_max_f32_e32 v66, v46, v47
	s_nop 1
	v_max_f32_e32 v67, v48, v49
	v_max3_f32 v33, v33, v66, v67

.LBB0_1402:
	s_add_u32 s0, s46, 0x8bfe000
	s_addc_u32 s1, s47, 0
	v_lshlrev_b64 v[34:35], 11, v[112:113]
	v_lshl_add_u64 v[34:35], s[0:1], 0, v[34:35]
	v_lshl_add_u64 v[34:35], v[34:35], 0, s[12:13]
	v_lshl_add_u64 v[34:35], v[192:193], 1, v[34:35]
	v_mov_b64_e32 v[36:37], v[160:161]
	v_mov_b64_e32 v[38:39], v[162:163]
	v_mov_b64_e32 v[40:41], v[164:165]
	v_mov_b64_e32 v[42:43], v[166:167]
	v_mov_b64_e32 v[44:45], v[168:169]
	v_cmp_lt_i32_e32 vcc, v222, v221
	v_mov_b64_e32 v[46:47], v[170:171]
	v_lshlrev_b32_e32 v140, 3, v69
	v_cndmask_b32_e32 v33, v220, v222, vcc
	v_lshlrev_b32_e32 v210, 2, v33
	ds_bpermute_b32 v33, v210, v32
	s_waitcnt lgkmcnt(0)
	v_add_f32_e32 v50, v32, v33
	v_mov_b64_e32 v[32:33], v[172:173]
	v_mov_b64_e32 v[48:49], v[174:175]
	v_div_scale_f32 v51, s[4:5], v50, v50, 1.0
	v_rcp_f32_e32 v52, v51
	v_div_scale_f32 v53, vcc, 1.0, v50, 1.0
	v_readlane_b32 s4, v254, 52
	v_fma_f32 v54, -v51, v52, 1.0
	v_fmac_f32_e32 v52, v54, v52
	v_mul_f32_e32 v54, v53, v52
	v_fma_f32 v55, -v51, v54, v53
	v_fmac_f32_e32 v54, v55, v52
	v_fma_f32 v51, -v51, v54, v53
	v_div_fmas_f32 v51, v51, v52, v54
	v_div_fixup_f32 v50, v51, v50, 1.0
	v_pk_mul_f32 v[16:17], v[16:17], v[50:51] op_sel_hi:[1,0]
	v_pk_mul_f32 v[18:19], v[18:19], v[50:51] op_sel_hi:[1,0]
	v_pk_mul_f32 v[0:1], v[0:1], v[50:51] op_sel_hi:[1,0]
	v_pk_mul_f32 v[2:3], v[2:3], v[50:51] op_sel_hi:[1,0]
	v_pk_mul_f32 v[20:21], v[20:21], v[50:51] op_sel_hi:[1,0]
	v_pk_mul_f32 v[22:23], v[22:23], v[50:51] op_sel_hi:[1,0]
	v_pk_mul_f32 v[24:25], v[24:25], v[50:51] op_sel_hi:[1,0]
	v_pk_mul_f32 v[26:27], v[26:27], v[50:51] op_sel_hi:[1,0]
	v_pk_mul_f32 v[28:29], v[28:29], v[50:51] op_sel_hi:[1,0]
	v_pk_mul_f32 v[30:31], v[30:31], v[50:51] op_sel_hi:[1,0]
	v_pk_mul_f32 v[4:5], v[4:5], v[50:51] op_sel_hi:[1,0]
	v_readlane_b32 s5, v254, 53
	s_andn2_b64 vcc, exec, s[4:5]
	s_waitcnt vmcnt(7)
	v_lshlrev_b32_e32 v52, 16, v36
	v_and_b32_e32 v53, 0xffff0000, v36
	v_lshlrev_b32_e32 v36, 16, v37
	v_and_b32_e32 v37, 0xffff0000, v37
	s_waitcnt vmcnt(3)
	v_lshlrev_b32_e32 v60, 16, v44
	v_and_b32_e32 v61, 0xffff0000, v44
	v_lshlrev_b32_e32 v44, 16, v45
	v_and_b32_e32 v45, 0xffff0000, v45
	v_lshlrev_b32_e32 v54, 16, v38
	v_and_b32_e32 v55, 0xffff0000, v38
	v_lshlrev_b32_e32 v38, 16, v39
	v_and_b32_e32 v39, 0xffff0000, v39
	v_lshlrev_b32_e32 v56, 16, v40
	v_and_b32_e32 v57, 0xffff0000, v40
	v_lshlrev_b32_e32 v40, 16, v41
	v_and_b32_e32 v41, 0xffff0000, v41
	v_lshlrev_b32_e32 v58, 16, v42
	v_and_b32_e32 v59, 0xffff0000, v42
	v_lshlrev_b32_e32 v42, 16, v43
	v_and_b32_e32 v43, 0xffff0000, v43
	v_pk_mul_f32 v[16:17], v[16:17], v[52:53]
	v_pk_mul_f32 v[18:19], v[18:19], v[36:37]
	v_pk_mul_f32 v[0:1], v[0:1], v[60:61]
	v_pk_mul_f32 v[2:3], v[2:3], v[44:45]
	v_pk_mul_f32 v[20:21], v[20:21], v[54:55]
	v_pk_mul_f32 v[22:23], v[22:23], v[38:39]
	v_pk_mul_f32 v[24:25], v[24:25], v[56:57]
	v_pk_mul_f32 v[26:27], v[26:27], v[40:41]
	v_pk_mul_f32 v[28:29], v[28:29], v[58:59]
	v_pk_mul_f32 v[30:31], v[30:31], v[42:43]
	v_cvt_pk_bf16_f32 v16, v16, v17
	v_cvt_pk_bf16_f32 v17, v18, v19
	v_cvt_pk_bf16_f32 v0, v0, v1
	v_cvt_pk_bf16_f32 v1, v2, v3
	v_cvt_pk_bf16_f32 v18, v20, v21
	v_cvt_pk_bf16_f32 v19, v22, v23
	v_cvt_pk_bf16_f32 v20, v24, v25
	v_cvt_pk_bf16_f32 v21, v26, v27
	v_cvt_pk_bf16_f32 v22, v28, v29
	v_cvt_pk_bf16_f32 v23, v30, v31
	global_store_dwordx2 v[34:35], v[16:17], off
	global_store_dwordx2 v[34:35], v[18:19], off offset:16
	global_store_dwordx2 v[34:35], v[20:21], off offset:32
	global_store_dwordx2 v[34:35], v[22:23], off offset:48
	global_store_dwordx2 v[34:35], v[0:1], off offset:64
	s_waitcnt vmcnt(7)
	v_lshlrev_b32_e32 v0, 16, v46
	v_and_b32_e32 v1, 0xffff0000, v46
	v_pk_mul_f32 v[0:1], v[4:5], v[0:1]
	v_pk_mul_f32 v[2:3], v[6:7], v[50:51] op_sel_hi:[1,0]
	v_lshlrev_b32_e32 v4, 16, v47
	v_and_b32_e32 v5, 0xffff0000, v47
	v_pk_mul_f32 v[2:3], v[2:3], v[4:5]
	v_cvt_pk_bf16_f32 v0, v0, v1
	v_cvt_pk_bf16_f32 v1, v2, v3
	global_store_dwordx2 v[34:35], v[0:1], off offset:80
	v_pk_mul_f32 v[0:1], v[8:9], v[50:51] op_sel_hi:[1,0]
	s_waitcnt vmcnt(7)
	v_lshlrev_b32_e32 v2, 16, v32
	v_and_b32_e32 v3, 0xffff0000, v32
	v_pk_mul_f32 v[0:1], v[0:1], v[2:3]
	v_pk_mul_f32 v[2:3], v[10:11], v[50:51] op_sel_hi:[1,0]
	v_lshlrev_b32_e32 v4, 16, v33
	v_and_b32_e32 v5, 0xffff0000, v33
	v_pk_mul_f32 v[2:3], v[2:3], v[4:5]
	v_cvt_pk_bf16_f32 v0, v0, v1
	v_cvt_pk_bf16_f32 v1, v2, v3
	global_store_dwordx2 v[34:35], v[0:1], off offset:96
	v_pk_mul_f32 v[0:1], v[12:13], v[50:51] op_sel_hi:[1,0]
	s_waitcnt vmcnt(7)
	v_lshlrev_b32_e32 v2, 16, v48
	v_and_b32_e32 v3, 0xffff0000, v48
	v_pk_mul_f32 v[0:1], v[0:1], v[2:3]
	v_pk_mul_f32 v[2:3], v[14:15], v[50:51] op_sel_hi:[1,0]
	v_lshlrev_b32_e32 v4, 16, v49
	v_and_b32_e32 v5, 0xffff0000, v49
	v_pk_mul_f32 v[2:3], v[2:3], v[4:5]
	v_cvt_pk_bf16_f32 v0, v0, v1
	v_cvt_pk_bf16_f32 v1, v2, v3
	global_store_dwordx2 v[34:35], v[0:1], off offset:112
	s_cbranch_vccnz .LBB0_1405
	s_lshl_b32 s4, s54, 5
	v_readlane_b32 s10, v254, 54
	s_add_i32 s5, s4, s10
	v_readlane_b32 s16, v255, 13
	v_readlane_b32 s11, v254, 55
	v_readlane_b32 s17, v255, 14
	s_add_u32 s10, s50, s16
	s_addc_u32 s11, s51, s17
	s_add_u32 s16, s36, s16
	s_addc_u32 s17, s37, s17
	v_lshlrev_b64 v[54:55], 10, v[132:133]
	v_lshl_add_u64 v[0:1], s[10:11], 0, v[54:55]
	v_mov_b32_e32 v111, v193
	v_lshl_add_u64 v[2:3], s[16:17], 0, v[54:55]
	v_lshl_add_u64 v[0:1], v[0:1], 0, v[110:111]
	v_lshl_add_u64 v[4:5], v[2:3], 0, v[110:111]
	global_load_dwordx4 v[0:3], v[0:1], off
	s_nop 0
	global_load_dwordx4 v[4:7], v[4:5], off
	v_or_b32_e32 v142, s5, v135
	v_ashrrev_i32_e32 v143, 31, v142
	v_readlane_b32 s18, v255, 33
	v_lshlrev_b64 v[8:9], 10, v[142:143]
	v_readlane_b32 s19, v255, 34
	v_lshl_add_u64 v[8:9], s[20:21], 0, v[8:9]
	s_mov_b32 s19, s13
	v_lshlrev_b64 v[234:235], 11, v[142:143]
	v_mov_b32_e32 v224, v140
	v_mov_b32_e32 v225, 0
	v_lshl_add_u64 v[234:235], s[0:1], 0, v[234:235]
	v_lshl_add_u64 v[234:235], v[234:235], 0, s[18:19]
	v_lshl_add_u64 v[234:235], v[234:235], 0, v[224:225]
	global_load_dwordx2 v[224:225], v[234:235], off
	global_load_dwordx2 v[226:227], v[234:235], off offset:16
	global_load_dwordx2 v[246:247], v[234:235], off offset:32
	global_load_dwordx2 v[248:249], v[234:235], off offset:48
	global_load_dwordx2 v[214:215], v[234:235], off offset:64
	global_load_dwordx2 v[216:217], v[234:235], off offset:80
	global_load_dwordx2 v[230:231], v[234:235], off offset:96
	global_load_dwordx2 v[232:233], v[234:235], off offset:112
	v_mov_b32_e32 v234, 0x7ffff800
	v_mov_b32_e32 v235, 0xffffff00
	v_lshl_add_u64 v[8:9], v[8:9], 0, s[18:19]
	v_lshlrev_b32_e32 v192, 1, v140
	v_lshl_add_u64 v[8:9], v[8:9], 0, v[192:193]
	global_load_dwordx4 v[92:95], v[8:9], off
	global_load_dwordx4 v[88:91], v[8:9], off offset:32
	global_load_dwordx4 v[84:87], v[8:9], off offset:64
	global_load_dwordx4 v[96:99], v[8:9], off offset:96
	v_readlane_b32 s16, v255, 15
	v_readlane_b32 s17, v255, 16
	s_add_u32 s10, s50, s16
	s_addc_u32 s11, s51, s17
	s_add_u32 s16, s36, s16
	v_lshl_add_u64 v[8:9], s[10:11], 0, v[54:55]
	s_addc_u32 s17, s37, s17
	v_lshl_add_u64 v[8:9], v[8:9], 0, v[110:111]
	v_lshl_add_u64 v[10:11], s[16:17], 0, v[54:55]
	v_lshl_add_u64 v[10:11], v[10:11], 0, v[110:111]
	global_load_dwordx4 v[16:19], v[8:9], off
	global_load_dwordx4 v[38:41], v[10:11], off
	v_readlane_b32 s16, v255, 17
	v_readlane_b32 s17, v255, 18
	s_add_u32 s10, s50, s16
	s_addc_u32 s11, s51, s17
	s_add_u32 s16, s36, s16
	v_lshl_add_u32 v237, v69, 4, 0
	s_movk_i32 s5, 0x90
	v_lshl_add_u64 v[8:9], s[10:11], 0, v[54:55]
	s_addc_u32 s17, s37, s17
	v_mad_u32_u24 v141, v209, s5, v237
	v_lshl_add_u64 v[8:9], v[8:9], 0, v[110:111]
	v_lshl_add_u64 v[10:11], s[16:17], 0, v[54:55]
	v_lshl_add_u64 v[10:11], v[10:11], 0, v[110:111]
	global_load_dwordx4 v[66:69], v[8:9], off
	global_load_dwordx4 v[70:73], v[10:11], off
	s_barrier
	v_mad_u32_u24 v238, v135, s5, v237
	v_readlane_b32 s10, v255, 19
	v_readlane_b32 s11, v255, 20
	s_waitcnt vmcnt(9)
	ds_write_b128 v207, v[0:3] offset:15360
	s_waitcnt vmcnt(8)
	ds_write_b128 v207, v[4:7] offset:24576
	s_waitcnt lgkmcnt(0)
	s_barrier
	ds_read_b128 v[0:3], v141 offset:15360
	ds_read_b128 v[42:45], v141 offset:15392
	s_waitcnt vmcnt(7) lgkmcnt(1)
	v_mfma_f32_32x32x16_bf16 v[0:15], v[0:3], v[92:95], 0
	ds_read_b128 v[20:23], v238 offset:15360
	ds_read_b128 v[46:49], v238 offset:15392
	s_waitcnt lgkmcnt(1)
	v_mfma_f32_32x32x16_bf16 v[22:37], v[20:23], v[92:95], 0
	v_lshl_add_u64 v[20:21], s[50:51], 0, v[54:55]
	v_lshl_add_u64 v[136:137], v[20:21], 0, v[110:111]
	s_waitcnt vmcnt(6)
	v_mfma_f32_32x32x16_bf16 v[0:15], v[42:45], v[88:91], v[0:15]
	s_waitcnt lgkmcnt(0)
	v_mfma_f32_32x32x16_bf16 v[22:37], v[46:49], v[88:91], v[22:37]
	ds_read_b128 v[42:45], v141 offset:15424
	ds_read_b128 v[46:49], v141 offset:15456
	s_waitcnt vmcnt(5) lgkmcnt(1)
	v_mfma_f32_32x32x16_bf16 v[0:15], v[42:45], v[84:87], v[0:15]
	ds_read_b128 v[42:45], v238 offset:15424
	ds_read_b128 v[50:53], v238 offset:15456
	s_waitcnt lgkmcnt(1)
	v_mfma_f32_32x32x16_bf16 v[22:37], v[42:45], v[84:87], v[22:37]
	v_lshl_add_u64 v[42:43], s[36:37], 0, v[54:55]
	v_lshl_add_u64 v[138:139], v[42:43], 0, v[110:111]
	v_lshlrev_b32_e32 v44, 1, v120
	v_mul_u32_u24_e32 v45, 0x90, v115
	v_add3_u32 v211, 0, v44, v45
	s_waitcnt vmcnt(4) lgkmcnt(0)
	v_mfma_f32_32x32x16_bf16 v[22:37], v[50:53], v[96:99], v[22:37]
	v_mfma_f32_32x32x16_bf16 v[0:15], v[46:49], v[96:99], v[0:15]
	s_nop 10
	v_max_f32_e32 v20, v23, v23
	v_max_f32_e32 v21, v22, v22
	v_max_f32_e32 v42, v25, v25
	v_max_f32_e32 v43, v24, v24
	v_max_f32_e32 v20, v21, v20
	v_max_f32_e32 v21, v43, v42
	v_max_f32_e32 v50, v27, v27
	v_max_f32_e32 v46, v1, v1
	v_max_f32_e32 v47, v0, v0
	v_max_f32_e32 v48, v3, v3
	v_max_f32_e32 v49, v2, v2
	v_max_f32_e32 v51, v26, v26
	v_max_f32_e32 v52, v29, v29
	v_max_f32_e32 v53, v28, v28
	v_max_f32_e32 v42, v47, v46
	v_max_f32_e32 v43, v49, v48
	v_max3_f32 v20, v20, s23, v21
	v_max_f32_e32 v54, v5, v5
	v_max_f32_e32 v55, v4, v4
	v_max_f32_e32 v56, v7, v7
	v_max_f32_e32 v57, v6, v6
	v_max_f32_e32 v46, v51, v50
	v_max_f32_e32 v47, v53, v52
	v_max3_f32 v20, v20, v42, v43
	v_max_f32_e32 v58, v31, v31
	v_max_f32_e32 v59, v30, v30
	v_max_f32_e32 v60, v33, v33
	v_max_f32_e32 v61, v32, v32
	v_max_f32_e32 v48, v55, v54
	v_max_f32_e32 v49, v57, v56
	v_max3_f32 v20, v20, v46, v47
	v_max_f32_e32 v62, v9, v9
	v_max_f32_e32 v63, v8, v8
	v_max_f32_e32 v64, v11, v11
	v_max_f32_e32 v65, v10, v10
	v_max_f32_e32 v50, v59, v58
	v_max_f32_e32 v51, v61, v60
	v_max3_f32 v20, v20, v48, v49
	v_max_f32_e32 v74, v35, v35
	v_max_f32_e32 v75, v34, v34
	v_max_f32_e32 v76, v37, v37
	v_max_f32_e32 v77, v36, v36
	v_max_f32_e32 v52, v63, v62
	v_max_f32_e32 v53, v65, v64
	v_max3_f32 v20, v20, v50, v51
	v_max_f32_e32 v78, v13, v13
	v_max_f32_e32 v79, v12, v12
	v_max_f32_e32 v80, v15, v15
	v_max_f32_e32 v81, v14, v14
	v_max_f32_e32 v54, v75, v74
	v_max_f32_e32 v55, v77, v76
	v_max3_f32 v20, v20, v52, v53
	v_max_f32_e32 v56, v79, v78
	v_max_f32_e32 v57, v81, v80
	v_max3_f32 v20, v20, v54, v55
	v_max3_f32 v46, v20, v56, v57
	ds_bpermute_b32 v47, v210, v46
	v_lshl_add_u64 v[42:43], v[136:137], 0, s[10:11]
	v_lshl_add_u64 v[20:21], v[138:139], 0, s[10:11]
	global_load_dwordx4 v[100:103], v[42:43], off
	global_load_dwordx4 v[104:107], v[20:21], off
	ds_read_b64_tr_b16 v[128:129], v211 offset:24576
	ds_read_b64_tr_b16 v[130:131], v211 offset:25728
	ds_read_b64_tr_b16 v[126:127], v211 offset:25792
	ds_read_b64_tr_b16 v[124:125], v211 offset:24640
	ds_read_b64_tr_b16 v[120:121], v211 offset:26880
	ds_read_b64_tr_b16 v[122:123], v211 offset:28032
	ds_read_b64_tr_b16 v[118:119], v211 offset:28096
	ds_read_b64_tr_b16 v[116:117], v211 offset:26944
	ds_read_b64_tr_b16 v[112:113], v211 offset:29184
	ds_read_b64_tr_b16 v[114:115], v211 offset:30336
	ds_read_b64_tr_b16 v[110:111], v211 offset:30400
	ds_read_b64_tr_b16 v[108:109], v211 offset:29248
	ds_read_b64_tr_b16 v[78:79], v211 offset:31488
	ds_read_b64_tr_b16 v[80:81], v211 offset:32640
	ds_read_b64_tr_b16 v[76:77], v211 offset:32704
	ds_read_b64_tr_b16 v[74:75], v211 offset:31552
	s_waitcnt lgkmcnt(14)
	v_max3_f32 v52, v46, v47, s23
	v_sub_f32_e32 v0, v0, v52
	v_exp_f32_e32 v150, v0
	v_sub_f32_e32 v0, v1, v52
	v_exp_f32_e32 v154, v0
	v_sub_f32_e32 v0, v2, v52
	v_exp_f32_e32 v144, v0
	v_sub_f32_e32 v0, v3, v52
	v_exp_f32_e32 v148, v0
	v_sub_f32_e32 v0, v26, v52
	v_exp_f32_e32 v152, v0
	v_sub_f32_e32 v0, v27, v52
	v_exp_f32_e32 v156, v0
	v_sub_f32_e32 v0, v28, v52
	v_exp_f32_e32 v160, v0
	v_sub_f32_e32 v0, v29, v52
	v_exp_f32_e32 v162, v0
	v_sub_f32_e32 v0, v4, v52
	v_exp_f32_e32 v158, v0
	v_sub_f32_e32 v0, v5, v52
	v_exp_f32_e32 v164, v0
	s_waitcnt vmcnt(5)
	ds_write_b128 v207, v[16:19] offset:33792
	s_waitcnt vmcnt(4)
	ds_write_b128 v207, v[38:41] offset:43008
	s_waitcnt lgkmcnt(0)
	s_barrier
	ds_read_b128 v[0:3], v141 offset:33792
	v_sub_f32_e32 v4, v6, v52
	v_exp_f32_e32 v168, v4
	v_sub_f32_e32 v4, v7, v52
	v_sub_f32_e32 v20, v22, v52
	v_exp_f32_e32 v170, v4
	v_sub_f32_e32 v4, v30, v52
	v_sub_f32_e32 v21, v23, v52
	v_sub_f32_e32 v22, v24, v52
	v_exp_f32_e32 v240, v20
	v_sub_f32_e32 v20, v25, v52
	v_exp_f32_e32 v172, v4
	ds_read_b128 v[4:7], v141 offset:33824
	v_exp_f32_e32 v239, v21
	v_exp_f32_e32 v82, v22
	v_exp_f32_e32 v146, v20
	v_sub_f32_e32 v38, v31, v52
	s_waitcnt lgkmcnt(1)
	v_mfma_f32_32x32x16_bf16 v[16:31], v[0:3], v[92:95], 0
	v_sub_f32_e32 v0, v32, v52
	v_exp_f32_e32 v174, v0
	v_sub_f32_e32 v0, v33, v52
	v_exp_f32_e32 v176, v0
	ds_read_b128 v[0:3], v141 offset:33856
	v_sub_f32_e32 v8, v8, v52
	v_exp_f32_e32 v180, v8
	s_waitcnt lgkmcnt(1)
	v_mfma_f32_32x32x16_bf16 v[16:31], v[4:7], v[88:91], v[16:31]
	v_sub_f32_e32 v4, v9, v52
	v_exp_f32_e32 v182, v4
	v_sub_f32_e32 v4, v10, v52
	v_exp_f32_e32 v184, v4
	ds_read_b128 v[4:7], v141 offset:33888
	v_sub_f32_e32 v8, v11, v52
	v_exp_f32_e32 v178, v38
	s_waitcnt lgkmcnt(1)
	v_mfma_f32_32x32x16_bf16 v[16:31], v[0:3], v[84:87], v[16:31]
	v_sub_f32_e32 v0, v34, v52
	v_exp_f32_e32 v186, v0
	v_sub_f32_e32 v0, v35, v52
	v_exp_f32_e32 v188, v0
	ds_read_b128 v[0:3], v238 offset:33792
	v_exp_f32_e32 v190, v8
	v_sub_f32_e32 v8, v36, v52
	s_waitcnt lgkmcnt(1)
	v_mfma_f32_32x32x16_bf16 v[16:31], v[4:7], v[96:99], v[16:31]
	v_sub_f32_e32 v4, v37, v52
	v_exp_f32_e32 v198, v4
	v_sub_f32_e32 v4, v12, v52
	v_exp_f32_e32 v200, v4
	ds_read_b128 v[4:7], v238 offset:33824
	v_exp_f32_e32 v196, v8
	v_sub_f32_e32 v8, v13, v52
	s_waitcnt lgkmcnt(1)
	v_mfma_f32_32x32x16_bf16 v[32:47], v[0:3], v[92:95], 0
	v_exp_f32_e32 v202, v8
	ds_read_b128 v[8:11], v238 offset:33856
	v_sub_f32_e32 v48, 0xf149f2ca, v52
	v_exp_f32_e32 v1, v48
	ds_read_b128 v[48:51], v238 offset:33888
	v_sub_f32_e32 v0, v14, v52
	v_exp_f32_e32 v204, v0
	s_waitcnt lgkmcnt(2)
	v_mfma_f32_32x32x16_bf16 v[32:47], v[4:7], v[88:91], v[32:47]
	v_sub_f32_e32 v0, v15, v52
	v_exp_f32_e32 v166, v0
	v_mul_f32_e32 v0, 0, v1
	v_mov_b32_e32 v1, v0
	v_mov_b32_e32 v2, v0
	v_mov_b32_e32 v3, v0
	v_mov_b32_e32 v4, v0
	s_waitcnt lgkmcnt(1)
	v_mfma_f32_32x32x16_bf16 v[32:47], v[8:11], v[84:87], v[32:47]
	v_mov_b32_e32 v5, v0
	v_mov_b32_e32 v6, v0
	v_mov_b32_e32 v7, v0
	v_mov_b32_e32 v8, v0
	v_mov_b32_e32 v9, v0
	v_mov_b32_e32 v10, v0
	v_mov_b32_e32 v11, v0
	s_waitcnt lgkmcnt(0)
	v_mfma_f32_32x32x16_bf16 v[32:47], v[48:51], v[96:99], v[32:47]
	v_max_f32_e32 v48, v18, v18
	v_mov_b32_e32 v12, v0
	v_cvt_pk_bf16_f32 v242, v240, v239
	v_cvt_pk_bf16_f32 v243, v82, v146
	v_cvt_pk_bf16_f32 v244, v152, v156
	v_cvt_pk_bf16_f32 v245, v160, v162
	s_mov_b32 s10, s18
	s_nop 4
	s_nop 1
	v_max_f32_e32 v13, v32, v33
	s_nop 1
	v_max_f32_e32 v14, v34, v35
	v_max3_f32 v13, v13, s23, v14
	s_nop 1
	v_max_f32_e32 v14, v16, v17
	v_max_f32_e32 v15, v19, v19
	v_max_f32_e32 v15, v48, v15
	v_max3_f32 v13, v13, v14, v15
	s_nop 1
	v_max_f32_e32 v14, v36, v37
	s_nop 1
	v_max_f32_e32 v15, v38, v39
	v_max3_f32 v13, v13, v14, v15
	s_nop 1
	v_max_f32_e32 v14, v20, v21
	s_nop 1
	v_max_f32_e32 v15, v22, v23
	v_max3_f32 v13, v13, v14, v15
	s_nop 1
	v_max_f32_e32 v14, v40, v41
	s_nop 1
	v_max_f32_e32 v15, v42, v43
	v_max3_f32 v13, v13, v14, v15
	s_nop 1
	v_max_f32_e32 v14, v24, v25
	s_nop 1
	v_max_f32_e32 v15, v26, v27
	v_max3_f32 v13, v13, v14, v15
	s_nop 1
	v_max_f32_e32 v14, v44, v45
	s_nop 1
	v_max_f32_e32 v15, v46, v47
	v_max3_f32 v13, v13, v14, v15
	s_nop 1
	v_max_f32_e32 v14, v28, v29
	s_nop 1
	v_max_f32_e32 v15, v30, v31
	v_max3_f32 v48, v13, v14, v15
	ds_bpermute_b32 v49, v210, v48
	v_mov_b32_e32 v13, v0
	v_mov_b32_e32 v14, v0
	v_mov_b32_e32 v15, v0
	v_writelane_b32 v255, s10, 33
	s_waitcnt lgkmcnt(0)
	v_max3_f32 v241, v52, v48, v49
	v_sub_f32_e32 v16, v16, v241
	v_exp_f32_e32 v145, v16
	v_sub_f32_e32 v16, v17, v241
	v_exp_f32_e32 v149, v16
	v_sub_f32_e32 v16, v18, v241
	v_exp_f32_e32 v153, v16
	v_sub_f32_e32 v16, v19, v241
	v_exp_f32_e32 v157, v16
	v_sub_f32_e32 v16, v36, v241
	v_exp_f32_e32 v161, v16
	v_sub_f32_e32 v16, v37, v241
	v_exp_f32_e32 v163, v16
	v_sub_f32_e32 v16, v38, v241
	v_exp_f32_e32 v159, v16
	v_sub_f32_e32 v16, v39, v241
	v_exp_f32_e32 v165, v16
	v_sub_f32_e32 v16, v20, v241
	v_exp_f32_e32 v169, v16
	v_sub_f32_e32 v16, v21, v241
	v_sub_f32_e32 v48, v52, v241
	v_mfma_f32_32x32x16_bf16 v[50:65], v[128:131], v[242:245], v[0:15]
	v_exp_f32_e32 v171, v16
	v_mov_b64_e32 v[16:17], v[14:15]
	v_sub_f32_e32 v18, v22, v241
	v_exp_f32_e32 v173, v18
	v_cvt_pk_bf16_f32 v18, v172, v178
	s_nop 1
	v_mov_b64_e32 v[14:15], v[12:13]
	v_mov_b64_e32 v[12:13], v[10:11]
	v_mov_b64_e32 v[10:11], v[8:9]
	v_mov_b64_e32 v[8:9], v[6:7]
	v_mov_b64_e32 v[6:7], v[4:5]
	v_mov_b64_e32 v[4:5], v[2:3]
	v_mov_b64_e32 v[2:3], v[0:1]
	v_cvt_pk_bf16_f32 v19, v174, v176
	v_cvt_pk_bf16_f32 v20, v186, v188
	v_mfma_f32_32x32x16_bf16 v[2:17], v[124:127], v[242:245], v[2:17]
	v_cvt_pk_bf16_f32 v21, v196, v198
	v_sub_f32_e32 v1, v23, v241
	v_exp_f32_e32 v179, v1
	v_sub_f32_e32 v1, v40, v241
	v_cvt_pk_bf16_f32 v22, v200, v202
	v_cvt_pk_bf16_f32 v23, v204, v166
	v_sub_f32_e32 v32, v32, v241
	v_mfma_f32_32x32x16_bf16 v[50:65], v[120:123], v[18:21], v[50:65]
	v_exp_f32_e32 v175, v1
	v_sub_f32_e32 v1, v41, v241
	v_exp_f32_e32 v83, v32
	v_sub_f32_e32 v32, v33, v241
	v_exp_f32_e32 v177, v1
	v_sub_f32_e32 v1, v42, v241
	v_exp_f32_e32 v147, v32
	v_mfma_f32_32x32x16_bf16 v[2:17], v[116:119], v[18:21], v[2:17]
	v_cvt_pk_bf16_f32 v18, v150, v154
	v_cvt_pk_bf16_f32 v19, v144, v148
	v_cvt_pk_bf16_f32 v20, v158, v164
	v_cvt_pk_bf16_f32 v21, v168, v170
	v_sub_f32_e32 v32, v34, v241
	v_exp_f32_e32 v181, v1
	v_sub_f32_e32 v1, v43, v241
	v_mfma_f32_32x32x16_bf16 v[50:65], v[112:115], v[18:21], v[50:65]
	v_exp_f32_e32 v151, v32
	v_sub_f32_e32 v32, v35, v241
	v_exp_f32_e32 v183, v1
	v_sub_f32_e32 v1, v24, v241
	v_exp_f32_e32 v155, v32
	v_exp_f32_e32 v185, v1
	v_sub_f32_e32 v1, v25, v241
	v_mfma_f32_32x32x16_bf16 v[2:17], v[108:111], v[18:21], v[2:17]
	v_cvt_pk_bf16_f32 v20, v180, v182
	v_cvt_pk_bf16_f32 v21, v184, v190
	v_exp_f32_e32 v18, v48
	v_exp_f32_e32 v191, v1
	v_sub_f32_e32 v1, v44, v241
	v_exp_f32_e32 v197, v1
	v_sub_f32_e32 v1, v45, v241
	v_mfma_f32_32x32x16_bf16 v[50:65], v[78:81], v[20:23], v[50:65]
	ds_read_b64_tr_b16 v[78:79], v211 offset:43008
	ds_read_b64_tr_b16 v[80:81], v211 offset:44160
	ds_read_b64_tr_b16 v[110:111], v211 offset:44224
	ds_read_b64_tr_b16 v[108:109], v211 offset:43072
	ds_read_b64_tr_b16 v[112:113], v211 offset:45312
	ds_read_b64_tr_b16 v[114:115], v211 offset:46464
	v_exp_f32_e32 v199, v1
	v_sub_f32_e32 v1, v46, v241
	v_exp_f32_e32 v201, v1
	v_sub_f32_e32 v1, v47, v241
	v_cvt_pk_bf16_f32 v116, v83, v147
	v_cvt_pk_bf16_f32 v117, v151, v155
	v_mfma_f32_32x32x16_bf16 v[2:17], v[74:77], v[20:23], v[2:17]
	v_cvt_pk_bf16_f32 v118, v161, v163
	v_cvt_pk_bf16_f32 v119, v159, v165
	v_mul_f32_e64 v48, v64, v18
	v_mul_f32_e64 v49, v65, v18
	v_mul_f32_e64 v46, v62, v18
	v_mul_f32_e64 v47, v63, v18
	v_pk_mul_f32 v[44:45], v[60:61], v[18:19] op_sel_hi:[1,0]
	v_pk_mul_f32 v[42:43], v[58:59], v[18:19] op_sel_hi:[1,0]
	v_pk_mul_f32 v[40:41], v[56:57], v[18:19] op_sel_hi:[1,0]
	v_pk_mul_f32 v[38:39], v[54:55], v[18:19] op_sel_hi:[1,0]
	v_pk_mul_f32 v[36:37], v[52:53], v[18:19] op_sel_hi:[1,0]
	v_pk_mul_f32 v[34:35], v[50:51], v[18:19] op_sel_hi:[1,0]
	v_pk_mul_f32 v[16:17], v[16:17], v[18:19] op_sel_hi:[1,0]
	v_pk_mul_f32 v[14:15], v[14:15], v[18:19] op_sel_hi:[1,0]
	v_pk_mul_f32 v[12:13], v[12:13], v[18:19] op_sel_hi:[1,0]
	v_pk_mul_f32 v[10:11], v[10:11], v[18:19] op_sel_hi:[1,0]
	v_pk_mul_f32 v[8:9], v[8:9], v[18:19] op_sel_hi:[1,0]
	v_pk_mul_f32 v[6:7], v[6:7], v[18:19] op_sel_hi:[1,0]
	v_pk_mul_f32 v[4:5], v[4:5], v[18:19] op_sel_hi:[1,0]
	v_pk_mul_f32 v[2:3], v[2:3], v[18:19] op_sel_hi:[1,0]
	s_waitcnt lgkmcnt(4)
	v_mfma_f32_32x32x16_bf16 v[34:49], v[78:81], v[116:119], v[34:49]
	v_exp_f32_e32 v203, v1
	ds_read_b64_tr_b16 v[22:23], v211 offset:46528
	ds_read_b64_tr_b16 v[20:21], v211 offset:45376
	v_cvt_pk_bf16_f32 v50, v175, v177
	v_cvt_pk_bf16_f32 v51, v181, v183
	v_cvt_pk_bf16_f32 v52, v197, v199
	v_cvt_pk_bf16_f32 v53, v201, v203
	v_sub_f32_e32 v1, v26, v241
	s_waitcnt lgkmcnt(4)
	v_mfma_f32_32x32x16_bf16 v[2:17], v[108:111], v[116:119], v[2:17]
	v_exp_f32_e32 v187, v1
	v_sub_f32_e32 v1, v27, v241
	ds_read_b64_tr_b16 v[24:25], v211 offset:47616
	ds_read_b64_tr_b16 v[26:27], v211 offset:48768
	v_exp_f32_e32 v189, v1
	v_sub_f32_e32 v1, v28, v241
	v_exp_f32_e32 v205, v1
	v_sub_f32_e32 v1, v29, v241
	s_waitcnt lgkmcnt(4)
	v_mfma_f32_32x32x16_bf16 v[34:49], v[112:115], v[50:53], v[34:49]
	v_exp_f32_e32 v167, v1
	v_sub_f32_e32 v1, v30, v241
	v_sub_f32_e32 v19, v31, v241
	v_exp_f32_e32 v1, v1
	v_exp_f32_e32 v19, v19
	v_cvt_pk_bf16_f32 v28, v185, v191
	v_cvt_pk_bf16_f32 v29, v187, v189
	s_waitcnt lgkmcnt(2)
	v_mfma_f32_32x32x16_bf16 v[2:17], v[20:23], v[50:53], v[2:17]
	ds_read_b64_tr_b16 v[22:23], v211 offset:48832
	ds_read_b64_tr_b16 v[20:21], v211 offset:47680
	v_cvt_pk_bf16_f32 v50, v145, v149
	v_cvt_pk_bf16_f32 v51, v153, v157
	v_cvt_pk_bf16_f32 v52, v169, v171
	v_cvt_pk_bf16_f32 v53, v173, v179
	v_cvt_pk_bf16_f32 v30, v205, v167
	v_cvt_pk_bf16_f32 v31, v1, v19
	s_waitcnt lgkmcnt(2)
	v_mfma_f32_32x32x16_bf16 v[34:49], v[24:27], v[50:53], v[34:49]
	ds_read_b64_tr_b16 v[24:25], v211 offset:49920
	ds_read_b64_tr_b16 v[26:27], v211 offset:51072
	v_writelane_b32 v255, s11, 34
	s_waitcnt lgkmcnt(2)
	v_mfma_f32_32x32x16_bf16 v[2:17], v[20:23], v[50:53], v[2:17]
	ds_read_b64_tr_b16 v[22:23], v211 offset:51136
	ds_read_b64_tr_b16 v[20:21], v211 offset:49984
	s_waitcnt vmcnt(3)
	ds_write_b128 v207, v[66:69] offset:15360
	s_waitcnt vmcnt(2)
	ds_write_b128 v207, v[70:73] offset:24576
	s_waitcnt lgkmcnt(0)
	s_barrier
	v_mfma_f32_32x32x16_bf16 v[34:49], v[24:27], v[28:31], v[34:49]
	v_mfma_f32_32x32x16_bf16 v[2:17], v[20:23], v[28:31], v[2:17]
	ds_read_b128 v[20:23], v141 offset:15360
	ds_read_b128 v[24:27], v141 offset:15392
	v_add_f32_e32 v28, 0, v240
	s_waitcnt lgkmcnt(1)
	v_mfma_f32_32x32x16_bf16 v[52:67], v[20:23], v[92:95], 0
	ds_read_b128 v[20:23], v141 offset:15424
	s_waitcnt lgkmcnt(1)
	v_mfma_f32_32x32x16_bf16 v[52:67], v[24:27], v[88:91], v[52:67]
	ds_read_b128 v[24:27], v141 offset:15456
	s_waitcnt lgkmcnt(1)
	v_mfma_f32_32x32x16_bf16 v[52:67], v[20:23], v[84:87], v[52:67]
	v_add_f32_e32 v20, v239, v28
	v_mov_b32_e32 v21, v193
	v_add_f32_e64 v20, v82, v20
	v_add_f32_e64 v21, v83, v21
	v_add_f32_e64 v20, v146, v20
	v_add_f32_e64 v21, v147, v21
	v_pk_add_f32 v[20:21], v[150:151], v[20:21]
	s_waitcnt lgkmcnt(0)
	v_mfma_f32_32x32x16_bf16 v[52:67], v[24:27], v[96:99], v[52:67]
	v_add_f32_e64 v28, v154, v20
	v_add_f32_e64 v29, v155, v21
	ds_read_b128 v[20:23], v238 offset:15360
	v_add_f32_e64 v24, v144, v28
	v_add_f32_e64 v25, v145, v29
	v_pk_add_f32 v[24:25], v[148:149], v[24:25]
	s_nop 0
	v_pk_add_f32 v[24:25], v[152:153], v[24:25]
	s_nop 0
	v_pk_add_f32 v[24:25], v[156:157], v[24:25]
	s_nop 0
	v_pk_add_f32 v[24:25], v[160:161], v[24:25]
	s_nop 0
	v_pk_add_f32 v[28:29], v[162:163], v[24:25]
	ds_read_b128 v[24:27], v238 offset:15392
	s_waitcnt lgkmcnt(1)
	v_mfma_f32_32x32x16_bf16 v[68:83], v[20:23], v[92:95], 0
	v_add_f32_e64 v20, v158, v28
	v_add_f32_e64 v21, v159, v29
	v_add_f32_e64 v20, v164, v20
	v_add_f32_e64 v21, v165, v21
	v_add_f32_e64 v20, v168, v20
	v_add_f32_e64 v21, v169, v21
	v_pk_add_f32 v[20:21], v[170:171], v[20:21]
	s_waitcnt lgkmcnt(0)
	v_mfma_f32_32x32x16_bf16 v[68:83], v[24:27], v[88:91], v[68:83]
	v_add_f32_e64 v20, v172, v20
	v_add_f32_e64 v21, v173, v21
	v_add_f32_e64 v28, v178, v20
	v_add_f32_e64 v29, v179, v21
	ds_read_b128 v[20:23], v238 offset:15424
	v_pk_add_f32 v[24:25], v[174:175], v[28:29]
	v_mov_b32_e32 v175, v193
	v_pk_add_f32 v[24:25], v[176:177], v[24:25]
	s_nop 0
	v_pk_add_f32 v[24:25], v[180:181], v[24:25]
	s_nop 0
	v_pk_add_f32 v[24:25], v[182:183], v[24:25]
	s_nop 0
	v_pk_add_f32 v[24:25], v[184:185], v[24:25]
	s_nop 0
	v_pk_add_f32 v[28:29], v[190:191], v[24:25]
	ds_read_b128 v[24:27], v238 offset:15456
	s_waitcnt lgkmcnt(1)
	v_mfma_f32_32x32x16_bf16 v[68:83], v[20:23], v[84:87], v[68:83]
	v_add_f32_e64 v20, v186, v28
	v_add_f32_e64 v21, v187, v29
	v_add_f32_e64 v20, v188, v20
	v_add_f32_e64 v21, v189, v21
	v_add_f32_e64 v20, v196, v20
	v_add_f32_e64 v21, v197, v21
	v_pk_add_f32 v[20:21], v[198:199], v[20:21]
	s_waitcnt lgkmcnt(0)
	v_mfma_f32_32x32x16_bf16 v[68:83], v[24:27], v[96:99], v[68:83]
	v_max_f32_e32 v25, v54, v54
	v_add_f32_e64 v20, v200, v20
	v_add_f32_e64 v21, v201, v21
	v_add_f32_e64 v20, v202, v20
	v_add_f32_e64 v21, v203, v21
	v_pk_add_f32 v[20:21], v[204:205], v[20:21]
	s_nop 5
	s_nop 1
	v_max_f32_e32 v22, v68, v69
	s_nop 1
	v_max_f32_e32 v23, v70, v71
	v_max3_f32 v22, v22, s23, v23
	s_nop 1
	v_max_f32_e32 v23, v52, v53
	v_max_f32_e32 v24, v55, v55
	v_max_f32_e32 v24, v25, v24
	v_max3_f32 v22, v22, v23, v24
	s_nop 1
	v_max_f32_e32 v23, v72, v73
	s_nop 1
	v_max_f32_e32 v24, v74, v75
	v_max3_f32 v22, v22, v23, v24
	s_nop 1
	v_max_f32_e32 v23, v56, v57
	s_nop 1
	v_max_f32_e32 v24, v58, v59
	v_max3_f32 v22, v22, v23, v24
	s_nop 1
	v_max_f32_e32 v23, v76, v77
	s_nop 1
	v_max_f32_e32 v24, v78, v79
	v_max3_f32 v22, v22, v23, v24
	s_nop 1
	v_max_f32_e32 v23, v60, v61
	s_nop 1
	v_max_f32_e32 v24, v62, v63
	v_max3_f32 v22, v22, v23, v24
	s_nop 1
	v_max_f32_e32 v23, v80, v81
	s_nop 1
	v_max_f32_e32 v24, v82, v83
	v_max3_f32 v22, v22, v23, v24
	s_nop 1
	v_max_f32_e32 v23, v64, v65
	s_nop 1
	v_max_f32_e32 v24, v66, v67
	v_max3_f32 v22, v22, v23, v24
	ds_bpermute_b32 v23, v210, v22
	v_pk_add_f32 v[20:21], v[166:167], v[20:21]
	s_waitcnt lgkmcnt(0)
	v_max3_f32 v125, v241, v22, v23
	v_pk_add_f32 v[0:1], v[0:1], v[20:21]
	v_sub_f32_e32 v22, v58, v125
	v_add_f32_e32 v1, v1, v19
	v_sub_f32_e32 v19, v68, v125
	v_fmac_f32_e32 v1, v0, v18
	v_sub_f32_e32 v18, v55, v125
	v_exp_f32_e32 v127, v19
	v_sub_f32_e32 v19, v69, v125
	v_exp_f32_e32 v124, v18
	v_sub_f32_e32 v18, v72, v125
	v_exp_f32_e32 v129, v19
	v_exp_f32_e32 v126, v18
	v_sub_f32_e32 v18, v73, v125
	v_exp_f32_e32 v128, v18
	v_sub_f32_e32 v18, v74, v125
	v_exp_f32_e32 v154, v18
	v_sub_f32_e32 v18, v75, v125
	v_add_f32_e32 v0, 0, v127
	v_exp_f32_e32 v156, v18
	v_sub_f32_e32 v18, v56, v125
	v_add_f32_e32 v174, v129, v0
	v_sub_f32_e32 v0, v70, v125
	v_exp_f32_e32 v130, v18
	v_sub_f32_e32 v18, v57, v125
	v_exp_f32_e32 v146, v0
	v_sub_f32_e32 v0, v71, v125
	v_exp_f32_e32 v144, v18
	ds_read_b64_tr_b16 v[176:177], v211 offset:24576
	ds_read_b64_tr_b16 v[178:179], v211 offset:25728
	ds_read_b64_tr_b16 v[182:183], v211 offset:25792
	ds_read_b64_tr_b16 v[180:181], v211 offset:24640
	ds_read_b64_tr_b16 v[120:121], v211 offset:26880
	ds_read_b64_tr_b16 v[122:123], v211 offset:28032
	ds_read_b64_tr_b16 v[114:115], v211 offset:28096
	ds_read_b64_tr_b16 v[112:113], v211 offset:26944
	ds_read_b64_tr_b16 v[116:117], v211 offset:29184
	ds_read_b64_tr_b16 v[118:119], v211 offset:30336
	ds_read_b64_tr_b16 v[110:111], v211 offset:30400
	ds_read_b64_tr_b16 v[108:109], v211 offset:29248
	ds_read_b64_tr_b16 v[72:73], v211 offset:31488
	ds_read_b64_tr_b16 v[74:75], v211 offset:32640
	ds_read_b64_tr_b16 v[70:71], v211 offset:32704
	ds_read_b64_tr_b16 v[68:69], v211 offset:31552
	s_waitcnt vmcnt(1)
	ds_write_b128 v207, v[100:103] offset:33792
	s_waitcnt vmcnt(0)
	ds_write_b128 v207, v[104:107] offset:43008
	s_waitcnt lgkmcnt(0)
	s_barrier
	ds_read_b128 v[18:21], v141 offset:33792
	v_exp_f32_e32 v100, v22
	v_sub_f32_e32 v22, v59, v125
	v_exp_f32_e32 v148, v0
	v_sub_f32_e32 v0, v52, v125
	v_exp_f32_e32 v102, v22
	v_sub_f32_e32 v22, v76, v125
	v_exp_f32_e32 v150, v0
	v_sub_f32_e32 v0, v53, v125
	v_exp_f32_e32 v76, v22
	v_sub_f32_e32 v22, v77, v125
	ds_read_b128 v[50:53], v141 offset:33824
	v_exp_f32_e32 v104, v22
	s_waitcnt lgkmcnt(1)
	v_mfma_f32_32x32x16_bf16 v[18:33], v[18:21], v[92:95], 0
	v_exp_f32_e32 v152, v0
	v_sub_f32_e32 v0, v54, v125
	v_sub_f32_e32 v54, v78, v125
	v_exp_f32_e32 v160, v54
	v_sub_f32_e32 v54, v79, v125
	v_exp_f32_e32 v164, v54
	v_sub_f32_e32 v54, v60, v125
	v_exp_f32_e32 v168, v54
	ds_read_b128 v[54:57], v141 offset:33856
	s_waitcnt lgkmcnt(1)
	v_mfma_f32_32x32x16_bf16 v[18:33], v[50:53], v[88:91], v[18:33]
	v_sub_f32_e32 v50, v61, v125
	v_exp_f32_e32 v172, v50
	v_sub_f32_e32 v50, v62, v125
	v_exp_f32_e32 v78, v50
	v_sub_f32_e32 v50, v63, v125
	v_exp_f32_e32 v106, v50
	ds_read_b128 v[50:53], v141 offset:33888
	s_waitcnt lgkmcnt(1)
	v_mfma_f32_32x32x16_bf16 v[18:33], v[54:57], v[84:87], v[18:33]
	v_sub_f32_e32 v54, v80, v125
	v_exp_f32_e32 v80, v54
	v_sub_f32_e32 v54, v81, v125
	v_exp_f32_e32 v158, v54
	v_sub_f32_e32 v54, v82, v125
	v_exp_f32_e32 v82, v54
	ds_read_b128 v[54:57], v238 offset:33792
	ds_read_b128 v[184:187], v238 offset:33824
	s_waitcnt lgkmcnt(2)
	v_mfma_f32_32x32x16_bf16 v[18:33], v[50:53], v[96:99], v[18:33]
	v_sub_f32_e32 v50, v83, v125
	v_exp_f32_e32 v162, v50
	v_sub_f32_e32 v50, v64, v125
	v_exp_f32_e32 v166, v50
	v_sub_f32_e32 v50, v65, v125
	v_exp_f32_e32 v170, v50
	ds_read_b128 v[188:191], v238 offset:33856
	s_waitcnt lgkmcnt(2)
	v_mfma_f32_32x32x16_bf16 v[50:65], v[54:57], v[92:95], 0
	v_sub_f32_e32 v131, v241, v125
	v_exp_f32_e32 v196, v131
	v_sub_f32_e32 v67, v67, v125
	v_exp_f32_e32 v94, v67
	v_max_f32_e32 v79, v20, v20
	v_mul_f32_e32 v92, v1, v196
	v_pk_mul_f32 v[48:49], v[48:49], v[196:197] op_sel_hi:[1,0]
	s_waitcnt lgkmcnt(1)
	v_mfma_f32_32x32x16_bf16 v[50:65], v[184:187], v[88:91], v[50:65]
	ds_read_b128 v[88:91], v238 offset:33888
	v_mul_f32_e64 v46, v46, v196
	v_mul_f32_e64 v47, v47, v196
	v_mul_f32_e64 v44, v44, v196
	v_mul_f32_e64 v45, v45, v196
	v_pk_mul_f32 v[42:43], v[42:43], v[196:197] op_sel_hi:[1,0]
	v_pk_mul_f32 v[40:41], v[40:41], v[196:197] op_sel_hi:[1,0]
	v_pk_mul_f32 v[38:39], v[38:39], v[196:197] op_sel_hi:[1,0]
	v_pk_mul_f32 v[36:37], v[36:37], v[196:197] op_sel_hi:[1,0]
	s_waitcnt lgkmcnt(1)
	v_mfma_f32_32x32x16_bf16 v[50:65], v[188:191], v[84:87], v[50:65]
	v_mul_f32_e64 v34, v34, v196
	v_mul_f32_e64 v35, v35, v196
	v_mul_f32_e64 v16, v16, v196
	v_mul_f32_e64 v17, v17, v196
	v_mul_f32_e64 v14, v14, v196
	v_mul_f32_e64 v15, v15, v196
	v_pk_mul_f32 v[12:13], v[12:13], v[196:197] op_sel_hi:[1,0]
	v_pk_mul_f32 v[10:11], v[10:11], v[196:197] op_sel_hi:[1,0]
	v_pk_mul_f32 v[8:9], v[8:9], v[196:197] op_sel_hi:[1,0]
	v_pk_mul_f32 v[6:7], v[6:7], v[196:197] op_sel_hi:[1,0]
	s_waitcnt lgkmcnt(0)
	v_mfma_f32_32x32x16_bf16 v[50:65], v[88:91], v[96:99], v[50:65]
	v_mul_f32_e64 v4, v4, v196
	v_mul_f32_e64 v5, v5, v196
	v_mul_f32_e64 v2, v2, v196
	v_mul_f32_e64 v3, v3, v196
	v_cvt_pk_bf16_f32 v84, v127, v129
	v_cvt_pk_bf16_f32 v85, v146, v148
	v_cvt_pk_bf16_f32 v86, v126, v128
	v_cvt_pk_bf16_f32 v87, v154, v156
	v_sub_f32_e32 v66, v66, v125
	s_nop 2
	s_nop 1
	v_max_f32_e32 v1, v50, v51
	s_nop 1
	v_max_f32_e32 v67, v52, v53
	v_max3_f32 v1, v1, s23, v67
	s_nop 1
	v_max_f32_e32 v67, v18, v19
	v_max_f32_e32 v77, v21, v21
	v_max_f32_e32 v77, v79, v77
	v_max3_f32 v1, v1, v67, v77
	s_nop 1
	v_max_f32_e32 v67, v54, v55
	s_nop 1
	v_max_f32_e32 v77, v56, v57
	v_max3_f32 v1, v1, v67, v77
	s_nop 1
	v_max_f32_e32 v67, v22, v23
	s_nop 1
	v_max_f32_e32 v77, v24, v25
	v_max3_f32 v1, v1, v67, v77
	s_nop 1
	v_max_f32_e32 v67, v58, v59
	s_nop 1
	v_max_f32_e32 v77, v60, v61
	v_max3_f32 v1, v1, v67, v77
	s_nop 1
	v_max_f32_e32 v67, v26, v27
	s_nop 1
	v_max_f32_e32 v77, v28, v29
	v_max3_f32 v1, v1, v67, v77
	s_nop 1
	v_max_f32_e32 v67, v62, v63
	s_nop 1
	v_max_f32_e32 v77, v64, v65
	v_max3_f32 v1, v1, v67, v77
	s_nop 1
	v_max_f32_e32 v67, v30, v31
	s_nop 1
	v_max_f32_e32 v77, v32, v33
	v_max3_f32 v1, v1, v67, v77
	ds_bpermute_b32 v67, v210, v1
	v_mfma_f32_32x32x16_bf16 v[34:49], v[176:179], v[84:87], v[34:49]
	v_exp_f32_e32 v0, v0
	v_exp_f32_e32 v66, v66
	v_mov_b32_e32 v141, v193
	s_waitcnt lgkmcnt(0)
	v_max3_f32 v96, v125, v1, v67
	v_sub_f32_e32 v1, v50, v96
	v_exp_f32_e32 v147, v1
	v_sub_f32_e32 v1, v51, v96
	v_mfma_f32_32x32x16_bf16 v[2:17], v[180:183], v[84:87], v[2:17]
	v_exp_f32_e32 v149, v1
	v_sub_f32_e32 v1, v52, v96
	v_exp_f32_e32 v151, v1
	v_sub_f32_e32 v1, v53, v96
	v_exp_f32_e32 v153, v1
	v_sub_f32_e32 v1, v18, v96
	v_sub_f32_e32 v18, v19, v96
	v_sub_f32_e32 v67, v125, v96
	v_exp_f32_e32 v125, v18
	v_sub_f32_e32 v18, v20, v96
	v_exp_f32_e32 v127, v18
	v_sub_f32_e32 v18, v21, v96
	v_exp_f32_e32 v129, v18
	v_sub_f32_e32 v18, v54, v96
	v_exp_f32_e32 v1, v1
	v_exp_f32_e32 v155, v18
	v_pk_add_f32 v[18:19], v[146:147], v[174:175]
	v_cvt_pk_bf16_f32 v50, v76, v104
	v_cvt_pk_bf16_f32 v51, v160, v164
	v_cvt_pk_bf16_f32 v52, v80, v158
	v_cvt_pk_bf16_f32 v53, v82, v162
	v_pk_add_f32 v[18:19], v[148:149], v[18:19]
	v_cvt_pk_bf16_f32 v21, v0, v124
	v_mfma_f32_32x32x16_bf16 v[34:49], v[120:123], v[50:53], v[34:49]
	v_add_f32_e64 v18, v150, v18
	v_add_f32_e64 v19, v151, v19
	v_cvt_pk_bf16_f32 v20, v150, v152
	v_add_f32_e64 v18, v152, v18
	v_add_f32_e64 v19, v153, v19
	v_pk_add_f32 v[18:19], v[0:1], v[18:19]
	v_sub_f32_e32 v0, v55, v96
	v_exp_f32_e32 v157, v0
	v_mfma_f32_32x32x16_bf16 v[2:17], v[112:115], v[50:53], v[2:17]
	v_sub_f32_e32 v0, v56, v96
	v_exp_f32_e32 v131, v0
	v_sub_f32_e32 v0, v57, v96
	v_exp_f32_e32 v145, v0
	v_sub_f32_e32 v0, v22, v96
	v_exp_f32_e32 v101, v0
	v_sub_f32_e32 v0, v23, v96
	v_cvt_pk_bf16_f32 v22, v130, v144
	v_cvt_pk_bf16_f32 v23, v100, v102
	v_exp_f32_e32 v103, v0
	v_sub_f32_e32 v0, v24, v96
	v_mfma_f32_32x32x16_bf16 v[34:49], v[116:119], v[20:23], v[34:49]
	v_exp_f32_e32 v77, v0
	v_sub_f32_e32 v0, v25, v96
	v_exp_f32_e32 v105, v0
	v_sub_f32_e32 v0, v58, v96
	v_exp_f32_e32 v161, v0
	v_sub_f32_e32 v0, v59, v96
	v_exp_f32_e32 v165, v0
	v_mfma_f32_32x32x16_bf16 v[2:17], v[108:111], v[20:23], v[2:17]
	v_sub_f32_e32 v0, v60, v96
	v_exp_f32_e32 v169, v0
	v_sub_f32_e32 v0, v61, v96
	v_exp_f32_e32 v173, v0
	v_sub_f32_e32 v0, v26, v96
	v_cvt_pk_bf16_f32 v24, v168, v172
	v_exp_f32_e32 v79, v0
	v_sub_f32_e32 v0, v27, v96
	v_cvt_pk_bf16_f32 v25, v78, v106
	v_cvt_pk_bf16_f32 v26, v166, v170
	v_cvt_pk_bf16_f32 v27, v66, v94
	v_exp_f32_e32 v107, v0
	v_sub_f32_e32 v0, v28, v96
	v_mfma_f32_32x32x16_bf16 v[34:49], v[72:75], v[24:27], v[34:49]
	v_exp_f32_e32 v81, v0
	v_sub_f32_e32 v0, v29, v96
	v_pk_add_f32 v[18:19], v[124:125], v[18:19]
	v_exp_f32_e32 v159, v0
	v_sub_f32_e32 v0, v62, v96
	v_pk_add_f32 v[18:19], v[126:127], v[18:19]
	v_exp_f32_e32 v83, v0
	v_mfma_f32_32x32x16_bf16 v[2:17], v[68:71], v[24:27], v[2:17]
	v_sub_f32_e32 v0, v63, v96
	v_sub_f32_e32 v20, v64, v96
	v_add_f32_e64 v18, v128, v18
	v_add_f32_e64 v19, v129, v19
	v_exp_f32_e32 v163, v0
	v_exp_f32_e32 v0, v67
	v_exp_f32_e32 v167, v20
	ds_read_b64_tr_b16 v[20:21], v211 offset:43008
	ds_read_b64_tr_b16 v[22:23], v211 offset:44160
	ds_read_b64_tr_b16 v[26:27], v211 offset:44224
	ds_read_b64_tr_b16 v[24:25], v211 offset:43072
	v_lshlrev_b64 v[28:29], 11, v[142:143]
	v_pk_add_f32 v[18:19], v[154:155], v[18:19]
	v_lshl_add_u64 v[28:29], s[0:1], 0, v[28:29]
	v_pk_add_f32 v[18:19], v[156:157], v[18:19]
	v_lshl_add_u64 v[28:29], v[28:29], 0, s[18:19]
	v_pk_add_f32 v[18:19], v[130:131], v[18:19]
	v_lshl_add_u64 v[28:29], v[28:29], 0, v[140:141]
	v_pk_add_f32 v[18:19], v[144:145], v[18:19]
	v_pk_mul_f32 v[48:49], v[48:49], v[0:1] op_sel_hi:[1,0]
	v_pk_mul_f32 v[46:47], v[46:47], v[0:1] op_sel_hi:[1,0]
	v_pk_mul_f32 v[44:45], v[44:45], v[0:1] op_sel_hi:[1,0]
	v_pk_mul_f32 v[42:43], v[42:43], v[0:1] op_sel_hi:[1,0]
	v_pk_mul_f32 v[40:41], v[40:41], v[0:1] op_sel_hi:[1,0]
	v_pk_mul_f32 v[38:39], v[38:39], v[0:1] op_sel_hi:[1,0]
	v_pk_mul_f32 v[36:37], v[36:37], v[0:1] op_sel_hi:[1,0]
	v_pk_mul_f32 v[34:35], v[34:35], v[0:1] op_sel_hi:[1,0]
	v_pk_mul_f32 v[16:17], v[16:17], v[0:1] op_sel_hi:[1,0]
	v_cvt_pk_bf16_f32 v50, v147, v149
	v_cvt_pk_bf16_f32 v51, v151, v153
	v_cvt_pk_bf16_f32 v52, v155, v157
	ds_read_b64_tr_b16 v[54:55], v211 offset:45312
	ds_read_b64_tr_b16 v[56:57], v211 offset:46464
	ds_read_b64_tr_b16 v[60:61], v211 offset:46528
	ds_read_b64_tr_b16 v[58:59], v211 offset:45376
	ds_read_b64_tr_b16 v[68:69], v211 offset:47616
	ds_read_b64_tr_b16 v[70:71], v211 offset:48768
	ds_read_b64_tr_b16 v[74:75], v211 offset:48832
	ds_read_b64_tr_b16 v[72:73], v211 offset:47680
	ds_read_b64_tr_b16 v[84:85], v211 offset:49920
	ds_read_b64_tr_b16 v[86:87], v211 offset:51072
	ds_read_b64_tr_b16 v[90:91], v211 offset:51136
	ds_read_b64_tr_b16 v[88:89], v211 offset:49984
	s_waitcnt lgkmcnt(0)
	s_barrier
	v_mov_b64_e32 v[62:63], v[224:225]
	v_cvt_pk_bf16_f32 v53, v131, v145
	v_pk_mul_f32 v[14:15], v[14:15], v[0:1] op_sel_hi:[1,0]
	v_pk_mul_f32 v[12:13], v[12:13], v[0:1] op_sel_hi:[1,0]
	v_pk_mul_f32 v[10:11], v[10:11], v[0:1] op_sel_hi:[1,0]
	v_pk_mul_f32 v[8:9], v[8:9], v[0:1] op_sel_hi:[1,0]
	v_pk_mul_f32 v[6:7], v[6:7], v[0:1] op_sel_hi:[1,0]
	v_pk_mul_f32 v[4:5], v[4:5], v[0:1] op_sel_hi:[1,0]
	v_pk_mul_f32 v[2:3], v[2:3], v[0:1] op_sel_hi:[1,0]
	v_pk_add_f32 v[18:19], v[100:101], v[18:19]
	v_mfma_f32_32x32x16_bf16 v[34:49], v[20:23], v[50:53], v[34:49]
	v_add_f32_e64 v18, v102, v18
	v_add_f32_e64 v19, v103, v19
	v_sub_f32_e32 v20, v65, v96
	v_add_f32_e64 v18, v76, v18
	v_add_f32_e64 v19, v77, v19
	v_exp_f32_e32 v171, v20
	v_pk_add_f32 v[18:19], v[104:105], v[18:19]
	v_cvt_pk_bf16_f32 v20, v161, v165
	v_pk_add_f32 v[18:19], v[160:161], v[18:19]
	v_mfma_f32_32x32x16_bf16 v[2:17], v[24:27], v[50:53], v[2:17]
	v_mov_b64_e32 v[24:25], v[226:227]
	v_add_f32_e64 v18, v164, v18
	v_add_f32_e64 v19, v165, v19
	v_sub_f32_e32 v26, v30, v96
	v_add_f32_e64 v18, v168, v18
	v_add_f32_e64 v19, v169, v19
	v_cvt_pk_bf16_f32 v21, v169, v173
	v_pk_add_f32 v[18:19], v[172:173], v[18:19]
	v_cvt_pk_bf16_f32 v22, v83, v163
	v_cvt_pk_bf16_f32 v23, v167, v171
	v_exp_f32_e32 v67, v26
	v_mov_b64_e32 v[26:27], v[246:247]
	v_mfma_f32_32x32x16_bf16 v[34:49], v[54:57], v[20:23], v[34:49]
	v_sub_f32_e32 v30, v31, v96
	v_exp_f32_e32 v95, v30
	v_sub_f32_e32 v30, v32, v96
	v_exp_f32_e32 v93, v30
	v_sub_f32_e32 v30, v33, v96
	v_exp_f32_e32 v50, v30
	v_mov_b64_e32 v[30:31], v[248:249]
	v_mfma_f32_32x32x16_bf16 v[2:17], v[58:61], v[20:23], v[2:17]
	v_add_f32_e64 v22, v78, v18
	v_add_f32_e64 v23, v79, v19
	v_cvt_pk_bf16_f32 v18, v1, v125
	v_add_f32_e64 v22, v106, v22
	v_add_f32_e64 v23, v107, v23
	v_cvt_pk_bf16_f32 v19, v127, v129
	v_pk_add_f32 v[22:23], v[80:81], v[22:23]
	v_cvt_pk_bf16_f32 v20, v101, v103
	v_pk_add_f32 v[22:23], v[158:159], v[22:23]
	v_cvt_pk_bf16_f32 v21, v77, v105
	v_pk_add_f32 v[22:23], v[82:83], v[22:23]
	v_mov_b64_e32 v[32:33], v[214:215]
	v_pk_add_f32 v[22:23], v[162:163], v[22:23]
	v_mfma_f32_32x32x16_bf16 v[34:49], v[68:71], v[18:21], v[34:49]
	v_add_f32_e64 v22, v166, v22
	v_add_f32_e64 v23, v167, v23
	v_add_f32_e64 v22, v170, v22
	v_add_f32_e64 v23, v171, v23
	v_mfma_f32_32x32x16_bf16 v[2:17], v[72:75], v[18:21], v[2:17]
	v_add_f32_e64 v18, v66, v22
	v_add_f32_e64 v19, v67, v23
	v_cvt_pk_bf16_f32 v20, v67, v95
	v_add_f32_e64 v18, v94, v18
	v_add_f32_e64 v19, v95, v19
	v_cvt_pk_bf16_f32 v21, v93, v50
	v_pk_add_f32 v[22:23], v[92:93], v[18:19]
	v_cvt_pk_bf16_f32 v18, v79, v107
	v_add_f32_e32 v23, v23, v50
	v_fmac_f32_e32 v23, v22, v0
	v_mov_b64_e32 v[0:1], v[216:217]
	v_cvt_pk_bf16_f32 v19, v81, v159
	ds_bpermute_b32 v22, v210, v23
	s_waitcnt lgkmcnt(0)
	v_add_f32_e32 v22, v23, v22
	v_mfma_f32_32x32x16_bf16 v[34:49], v[84:87], v[18:21], v[34:49]
	v_div_scale_f32 v23, s[10:11], v22, v22, 1.0
	v_rcp_f32_e32 v50, v23
	v_readlane_b32 s10, v254, 56
	v_readlane_b32 s11, v254, 57
	v_fma_f32 v51, -v23, v50, 1.0
	v_mfma_f32_32x32x16_bf16 v[2:17], v[88:91], v[18:21], v[2:17]
	v_mov_b64_e32 v[18:19], v[230:231]
	v_mov_b64_e32 v[20:21], v[232:233]
	v_fmac_f32_e32 v50, v51, v50
	v_div_scale_f32 v51, vcc, 1.0, v22, 1.0
	v_mul_f32_e32 v52, v51, v50
	v_fma_f32 v53, -v23, v52, v51
	v_fmac_f32_e32 v52, v53, v50
	v_fma_f32 v23, -v23, v52, v51
	v_div_fmas_f32 v23, v23, v50, v52
	v_div_fixup_f32 v22, v23, v22, 1.0
	v_pk_mul_f32 v[34:35], v[34:35], v[22:23] op_sel_hi:[1,0]
	s_waitcnt vmcnt(7)
	v_lshlrev_b32_e32 v50, 16, v62
	v_and_b32_e32 v51, 0xffff0000, v62
	v_pk_mul_f32 v[34:35], v[34:35], v[50:51]
	v_pk_mul_f32 v[36:37], v[36:37], v[22:23] op_sel_hi:[1,0]
	v_lshlrev_b32_e32 v50, 16, v63
	v_and_b32_e32 v51, 0xffff0000, v63
	v_pk_mul_f32 v[36:37], v[36:37], v[50:51]
	v_cvt_pk_bf16_f32 v34, v34, v35
	v_cvt_pk_bf16_f32 v35, v36, v37
	global_store_dwordx2 v[28:29], v[34:35], off
	v_pk_mul_f32 v[34:35], v[38:39], v[22:23] op_sel_hi:[1,0]
	s_waitcnt vmcnt(7)
	v_lshlrev_b32_e32 v36, 16, v24
	v_and_b32_e32 v37, 0xffff0000, v24
	v_pk_mul_f32 v[34:35], v[34:35], v[36:37]
	v_lshlrev_b32_e32 v36, 16, v25
	v_cvt_pk_bf16_f32 v24, v34, v35
	v_pk_mul_f32 v[34:35], v[40:41], v[22:23] op_sel_hi:[1,0]
	v_and_b32_e32 v37, 0xffff0000, v25
	v_pk_mul_f32 v[34:35], v[34:35], v[36:37]
	v_pk_mul_f32 v[2:3], v[2:3], v[22:23] op_sel_hi:[1,0]
	v_cvt_pk_bf16_f32 v25, v34, v35
	global_store_dwordx2 v[28:29], v[24:25], off offset:16
	v_pk_mul_f32 v[24:25], v[42:43], v[22:23] op_sel_hi:[1,0]
	s_waitcnt vmcnt(7)
	v_lshlrev_b32_e32 v34, 16, v26
	v_and_b32_e32 v35, 0xffff0000, v26
	v_pk_mul_f32 v[24:25], v[24:25], v[34:35]
	v_pk_mul_f32 v[34:35], v[44:45], v[22:23] op_sel_hi:[1,0]
	v_lshlrev_b32_e32 v26, 16, v27
	v_and_b32_e32 v27, 0xffff0000, v27
	v_pk_mul_f32 v[26:27], v[34:35], v[26:27]
	v_cvt_pk_bf16_f32 v24, v24, v25
	v_cvt_pk_bf16_f32 v25, v26, v27
	global_store_dwordx2 v[28:29], v[24:25], off offset:32
	v_pk_mul_f32 v[24:25], v[46:47], v[22:23] op_sel_hi:[1,0]
	s_waitcnt vmcnt(7)
	v_lshlrev_b32_e32 v26, 16, v30
	v_and_b32_e32 v27, 0xffff0000, v30
	v_pk_mul_f32 v[24:25], v[24:25], v[26:27]
	v_pk_mul_f32 v[26:27], v[48:49], v[22:23] op_sel_hi:[1,0]
	v_lshlrev_b32_e32 v30, 16, v31
	v_and_b32_e32 v31, 0xffff0000, v31
	v_pk_mul_f32 v[26:27], v[26:27], v[30:31]
	v_cvt_pk_bf16_f32 v24, v24, v25
	v_cvt_pk_bf16_f32 v25, v26, v27
	global_store_dwordx2 v[28:29], v[24:25], off offset:48
	s_waitcnt vmcnt(7)
	v_lshlrev_b32_e32 v24, 16, v32
	v_and_b32_e32 v25, 0xffff0000, v32
	v_pk_mul_f32 v[2:3], v[2:3], v[24:25]
	v_pk_mul_f32 v[4:5], v[4:5], v[22:23] op_sel_hi:[1,0]
	v_lshlrev_b32_e32 v24, 16, v33
	v_and_b32_e32 v25, 0xffff0000, v33
	v_pk_mul_f32 v[4:5], v[4:5], v[24:25]
	v_cvt_pk_bf16_f32 v2, v2, v3
	v_cvt_pk_bf16_f32 v3, v4, v5
	global_store_dwordx2 v[28:29], v[2:3], off offset:64
	v_pk_mul_f32 v[2:3], v[6:7], v[22:23] op_sel_hi:[1,0]
	s_waitcnt vmcnt(7)
	v_lshlrev_b32_e32 v4, 16, v0
	v_and_b32_e32 v5, 0xffff0000, v0
	v_pk_mul_f32 v[2:3], v[2:3], v[4:5]
	v_lshlrev_b32_e32 v4, 16, v1
	v_cvt_pk_bf16_f32 v0, v2, v3
	v_pk_mul_f32 v[2:3], v[8:9], v[22:23] op_sel_hi:[1,0]
	v_and_b32_e32 v5, 0xffff0000, v1
	v_pk_mul_f32 v[2:3], v[2:3], v[4:5]
	s_andn2_b64 vcc, exec, s[10:11]
	v_cvt_pk_bf16_f32 v1, v2, v3
	global_store_dwordx2 v[28:29], v[0:1], off offset:80
	v_pk_mul_f32 v[0:1], v[10:11], v[22:23] op_sel_hi:[1,0]
	s_waitcnt vmcnt(7)
	v_lshlrev_b32_e32 v2, 16, v18
	v_and_b32_e32 v3, 0xffff0000, v18
	v_pk_mul_f32 v[0:1], v[0:1], v[2:3]
	v_pk_mul_f32 v[2:3], v[12:13], v[22:23] op_sel_hi:[1,0]
	v_lshlrev_b32_e32 v4, 16, v19
	v_and_b32_e32 v5, 0xffff0000, v19
	v_pk_mul_f32 v[2:3], v[2:3], v[4:5]
	v_cvt_pk_bf16_f32 v0, v0, v1
	v_cvt_pk_bf16_f32 v1, v2, v3
	global_store_dwordx2 v[28:29], v[0:1], off offset:96
	v_pk_mul_f32 v[0:1], v[14:15], v[22:23] op_sel_hi:[1,0]
	s_waitcnt vmcnt(7)
	v_lshlrev_b32_e32 v2, 16, v20
	v_and_b32_e32 v3, 0xffff0000, v20
	v_pk_mul_f32 v[0:1], v[0:1], v[2:3]
	v_pk_mul_f32 v[2:3], v[16:17], v[22:23] op_sel_hi:[1,0]
	v_lshlrev_b32_e32 v4, 16, v21
	v_and_b32_e32 v5, 0xffff0000, v21
	v_pk_mul_f32 v[2:3], v[2:3], v[4:5]
	v_cvt_pk_bf16_f32 v0, v0, v1
	v_cvt_pk_bf16_f32 v1, v2, v3
	global_store_dwordx2 v[28:29], v[0:1], off offset:112
	s_cbranch_vccnz .LBB0_1405
	v_readlane_b32 s5, v254, 58
	s_add_i32 s4, s4, s5
	v_lshlrev_b64 v[0:1], 9, v[132:133]
	v_or_b32_e32 v132, s4, v135
	v_readlane_b32 s10, v255, 21
	v_ashrrev_i32_e32 v133, 31, v132
	v_readlane_b32 s16, v255, 35
	s_add_u32 s4, s50, s10
	v_lshlrev_b64 v[2:3], 10, v[132:133]
	v_readlane_b32 s17, v255, 36
	s_addc_u32 s5, s51, 0
	v_lshl_add_u64 v[2:3], s[20:21], 0, v[2:3]
	s_mov_b32 s17, s13
	v_lshlrev_b64 v[204:205], 11, v[132:133]
	v_lshlrev_b32_e32 v224, 1, v206
	v_mov_b32_e32 v225, 0
	v_lshl_add_u64 v[204:205], s[0:1], 0, v[204:205]
	v_lshl_add_u64 v[204:205], v[204:205], 0, s[16:17]
	v_lshl_add_u64 v[204:205], v[204:205], 0, v[224:225]
	global_load_dwordx2 v[238:239], v[204:205], off
	global_load_dwordx2 v[240:241], v[204:205], off offset:16
	global_load_dwordx2 v[242:243], v[204:205], off offset:32
	global_load_dwordx2 v[244:245], v[204:205], off offset:48
	global_load_dwordx2 v[246:247], v[204:205], off offset:64
	global_load_dwordx2 v[248:249], v[204:205], off offset:80
	global_load_dwordx2 v[224:225], v[204:205], off offset:96
	global_load_dwordx2 v[226:227], v[204:205], off offset:112
	s_add_u32 s10, s36, s10
	v_lshl_add_u64 v[2:3], v[2:3], 0, s[16:17]
	s_addc_u32 s11, s37, 0
	v_lshlrev_b64 v[10:11], 1, v[0:1]
	v_lshl_add_u64 v[8:9], v[2:3], 0, v[192:193]
	v_lshl_add_u64 v[0:1], s[4:5], 0, v[10:11]
	v_lshlrev_b32_e32 v192, 1, v134
	v_lshl_add_u64 v[2:3], s[10:11], 0, v[10:11]
	v_lshl_add_u64 v[0:1], v[0:1], 0, v[192:193]
	v_lshl_add_u64 v[4:5], v[2:3], 0, v[192:193]
	global_load_dwordx4 v[0:3], v[0:1], off
	s_nop 0
	global_load_dwordx4 v[4:7], v[4:5], off
	s_nop 0
	global_load_dwordx4 v[92:95], v[8:9], off
	global_load_dwordx4 v[88:91], v[8:9], off offset:32
	global_load_dwordx4 v[84:87], v[8:9], off offset:64
	global_load_dwordx4 v[96:99], v[8:9], off offset:96
	v_readlane_b32 s10, v255, 22
	s_add_u32 s4, s50, s10
	s_addc_u32 s5, s51, 0
	s_add_u32 s10, s36, s10
	v_mul_u32_u24_e32 v12, 0x90, v209
	v_lshl_add_u64 v[8:9], s[4:5], 0, v[10:11]
	s_addc_u32 s11, s37, 0
	v_add_u32_e32 v196, v237, v12
	v_lshl_add_u64 v[8:9], v[8:9], 0, v[192:193]
	v_lshl_add_u64 v[12:13], s[10:11], 0, v[10:11]
	v_lshl_add_u64 v[12:13], v[12:13], 0, v[192:193]
	global_load_dwordx4 v[16:19], v[8:9], off
	global_load_dwordx4 v[38:41], v[12:13], off
	v_readlane_b32 s10, v255, 23
	s_add_u32 s4, s50, s10
	s_addc_u32 s5, s51, 0
	s_add_u32 s10, s36, s10
	v_lshl_add_u64 v[8:9], s[4:5], 0, v[10:11]
	s_addc_u32 s11, s37, 0
	v_lshl_add_u64 v[8:9], v[8:9], 0, v[192:193]
	v_lshl_add_u64 v[10:11], s[10:11], 0, v[10:11]
	v_lshl_add_u64 v[10:11], v[10:11], 0, v[192:193]
	global_load_dwordx4 v[66:69], v[8:9], off
	global_load_dwordx4 v[70:73], v[10:11], off
	s_barrier
	v_add_u32_e32 v197, v237, v208
	v_readlane_b32 s4, v255, 37
	v_readlane_b32 s5, v255, 38
	s_mov_b32 s5, s13
	s_mov_b32 s10, s4
	v_writelane_b32 v255, s10, 37
	s_waitcnt vmcnt(9)
	ds_write_b128 v207, v[0:3] offset:15360
	s_waitcnt vmcnt(8)
	ds_write_b128 v207, v[4:7] offset:24576
	s_waitcnt lgkmcnt(0)
	s_barrier
	ds_read_b128 v[0:3], v196 offset:15360
	ds_read_b128 v[42:45], v196 offset:15392
	s_waitcnt vmcnt(7) lgkmcnt(1)
	v_mfma_f32_32x32x16_bf16 v[0:15], v[0:3], v[92:95], 0
	ds_read_b128 v[20:23], v197 offset:15360
	ds_read_b128 v[46:49], v197 offset:15392
	v_writelane_b32 v255, s11, 38
	s_waitcnt lgkmcnt(1)
	v_mfma_f32_32x32x16_bf16 v[22:37], v[20:23], v[92:95], 0
	s_waitcnt vmcnt(6)
	v_mfma_f32_32x32x16_bf16 v[0:15], v[42:45], v[88:91], v[0:15]
	s_waitcnt lgkmcnt(0)
	v_mfma_f32_32x32x16_bf16 v[22:37], v[46:49], v[88:91], v[22:37]
	ds_read_b128 v[42:45], v196 offset:15424
	ds_read_b128 v[46:49], v196 offset:15456
	s_waitcnt vmcnt(5) lgkmcnt(1)
	v_mfma_f32_32x32x16_bf16 v[0:15], v[42:45], v[84:87], v[0:15]
	ds_read_b128 v[42:45], v197 offset:15424
	ds_read_b128 v[50:53], v197 offset:15456
	s_waitcnt lgkmcnt(1)
	v_mfma_f32_32x32x16_bf16 v[22:37], v[42:45], v[84:87], v[22:37]
	s_waitcnt vmcnt(4) lgkmcnt(0)
	v_mfma_f32_32x32x16_bf16 v[22:37], v[50:53], v[96:99], v[22:37]
	v_mfma_f32_32x32x16_bf16 v[0:15], v[46:49], v[96:99], v[0:15]
	s_nop 10
	v_max_f32_e32 v20, v23, v23
	v_max_f32_e32 v21, v22, v22
	v_max_f32_e32 v42, v25, v25
	v_max_f32_e32 v43, v24, v24
	v_max_f32_e32 v20, v21, v20
	v_max_f32_e32 v21, v43, v42
	v_max_f32_e32 v48, v27, v27
	v_max_f32_e32 v44, v1, v1
	v_max_f32_e32 v45, v0, v0
	v_max_f32_e32 v46, v3, v3
	v_max_f32_e32 v47, v2, v2
	v_max_f32_e32 v49, v26, v26
	v_max_f32_e32 v50, v29, v29
	v_max_f32_e32 v51, v28, v28
	v_max_f32_e32 v42, v45, v44
	v_max_f32_e32 v43, v47, v46
	v_max3_f32 v20, v20, s23, v21
	v_max_f32_e32 v52, v5, v5
	v_max_f32_e32 v53, v4, v4
	v_max_f32_e32 v54, v7, v7
	v_max_f32_e32 v55, v6, v6
	v_max_f32_e32 v44, v49, v48
	v_max_f32_e32 v45, v51, v50
	v_max3_f32 v20, v20, v42, v43
	v_max_f32_e32 v56, v31, v31
	v_max_f32_e32 v57, v30, v30
	v_max_f32_e32 v58, v33, v33
	v_max_f32_e32 v59, v32, v32
	v_max_f32_e32 v46, v53, v52
	v_max_f32_e32 v47, v55, v54
	v_max3_f32 v20, v20, v44, v45
	v_max_f32_e32 v60, v9, v9
	v_max_f32_e32 v61, v8, v8
	v_max_f32_e32 v62, v11, v11
	v_max_f32_e32 v63, v10, v10
	v_max_f32_e32 v48, v57, v56
	v_max_f32_e32 v49, v59, v58
	v_max3_f32 v20, v20, v46, v47
	v_max_f32_e32 v64, v35, v35
	v_max_f32_e32 v65, v34, v34
	v_max_f32_e32 v74, v37, v37
	v_max_f32_e32 v75, v36, v36
	v_max_f32_e32 v50, v61, v60
	v_max_f32_e32 v51, v63, v62
	v_max3_f32 v20, v20, v48, v49
	v_max_f32_e32 v76, v13, v13
	v_max_f32_e32 v77, v12, v12
	v_max_f32_e32 v78, v15, v15
	v_max_f32_e32 v79, v14, v14
	v_max_f32_e32 v52, v65, v64
	v_max_f32_e32 v53, v75, v74
	v_max3_f32 v20, v20, v50, v51
	v_max_f32_e32 v54, v77, v76
	v_max_f32_e32 v55, v79, v78
	v_max3_f32 v20, v20, v52, v53
	v_max3_f32 v44, v20, v54, v55
	ds_bpermute_b32 v45, v210, v44
	v_lshl_add_u64 v[42:43], v[136:137], 0, s[4:5]
	v_lshl_add_u64 v[20:21], v[138:139], 0, s[4:5]
	global_load_dwordx4 v[100:103], v[42:43], off
	global_load_dwordx4 v[104:107], v[20:21], off
	ds_read_b64_tr_b16 v[128:129], v211 offset:24576
	ds_read_b64_tr_b16 v[130:131], v211 offset:25728
	ds_read_b64_tr_b16 v[126:127], v211 offset:25792
	ds_read_b64_tr_b16 v[124:125], v211 offset:24640
	ds_read_b64_tr_b16 v[120:121], v211 offset:26880
	ds_read_b64_tr_b16 v[122:123], v211 offset:28032
	ds_read_b64_tr_b16 v[118:119], v211 offset:28096
	ds_read_b64_tr_b16 v[116:117], v211 offset:26944
	ds_read_b64_tr_b16 v[112:113], v211 offset:29184
	ds_read_b64_tr_b16 v[114:115], v211 offset:30336
	ds_read_b64_tr_b16 v[110:111], v211 offset:30400
	ds_read_b64_tr_b16 v[108:109], v211 offset:29248
	ds_read_b64_tr_b16 v[78:79], v211 offset:31488
	ds_read_b64_tr_b16 v[80:81], v211 offset:32640
	ds_read_b64_tr_b16 v[76:77], v211 offset:32704
	ds_read_b64_tr_b16 v[74:75], v211 offset:31552
	s_waitcnt lgkmcnt(14)
	v_max3_f32 v52, v44, v45, s23
	v_sub_f32_e32 v0, v0, v52
	v_exp_f32_e32 v140, v0
	v_sub_f32_e32 v0, v2, v52
	v_exp_f32_e32 v82, v0
	v_sub_f32_e32 v0, v3, v52
	v_exp_f32_e32 v134, v0
	v_sub_f32_e32 v0, v26, v52
	v_exp_f32_e32 v136, v0
	v_sub_f32_e32 v0, v27, v52
	v_exp_f32_e32 v146, v0
	v_sub_f32_e32 v0, v28, v52
	v_exp_f32_e32 v150, v0
	v_sub_f32_e32 v0, v29, v52
	v_exp_f32_e32 v152, v0
	v_sub_f32_e32 v0, v4, v52
	v_sub_f32_e32 v1, v1, v52
	v_exp_f32_e32 v148, v0
	v_sub_f32_e32 v0, v5, v52
	v_exp_f32_e32 v138, v1
	v_exp_f32_e32 v154, v0
	s_waitcnt vmcnt(5)
	ds_write_b128 v207, v[16:19] offset:33792
	s_waitcnt vmcnt(4)
	ds_write_b128 v207, v[38:41] offset:43008
	s_waitcnt lgkmcnt(0)
	s_barrier
	ds_read_b128 v[0:3], v196 offset:33792
	v_sub_f32_e32 v4, v6, v52
	v_exp_f32_e32 v158, v4
	v_sub_f32_e32 v4, v7, v52
	v_exp_f32_e32 v160, v4
	v_sub_f32_e32 v4, v30, v52
	v_sub_f32_e32 v20, v22, v52
	v_sub_f32_e32 v21, v23, v52
	v_sub_f32_e32 v22, v24, v52
	v_sub_f32_e32 v23, v25, v52
	v_exp_f32_e32 v162, v4
	ds_read_b128 v[4:7], v196 offset:33824
	v_exp_f32_e32 v192, v20
	v_exp_f32_e32 v198, v21
	v_exp_f32_e32 v144, v22
	v_exp_f32_e32 v142, v23
	v_sub_f32_e32 v38, v31, v52
	s_waitcnt lgkmcnt(1)
	v_mfma_f32_32x32x16_bf16 v[16:31], v[0:3], v[92:95], 0
	v_sub_f32_e32 v0, v32, v52
	v_exp_f32_e32 v164, v0
	v_sub_f32_e32 v0, v33, v52
	v_exp_f32_e32 v166, v0
	ds_read_b128 v[0:3], v196 offset:33856
	v_sub_f32_e32 v8, v8, v52
	v_exp_f32_e32 v170, v8
	s_waitcnt lgkmcnt(1)
	v_mfma_f32_32x32x16_bf16 v[16:31], v[4:7], v[88:91], v[16:31]
	v_sub_f32_e32 v4, v9, v52
	v_exp_f32_e32 v172, v4
	v_sub_f32_e32 v4, v10, v52
	v_exp_f32_e32 v174, v4
	ds_read_b128 v[4:7], v196 offset:33888
	v_sub_f32_e32 v8, v11, v52
	v_exp_f32_e32 v168, v38
	s_waitcnt lgkmcnt(1)
	v_mfma_f32_32x32x16_bf16 v[16:31], v[0:3], v[84:87], v[16:31]
	v_sub_f32_e32 v0, v34, v52
	v_exp_f32_e32 v176, v0
	v_sub_f32_e32 v0, v35, v52
	v_exp_f32_e32 v178, v0
	ds_read_b128 v[0:3], v197 offset:33792
	v_exp_f32_e32 v180, v8
	v_sub_f32_e32 v8, v36, v52
	s_waitcnt lgkmcnt(1)
	v_mfma_f32_32x32x16_bf16 v[16:31], v[4:7], v[96:99], v[16:31]
	v_sub_f32_e32 v4, v37, v52
	v_exp_f32_e32 v184, v4
	v_sub_f32_e32 v4, v12, v52
	v_exp_f32_e32 v186, v4
	ds_read_b128 v[4:7], v197 offset:33824
	v_exp_f32_e32 v182, v8
	v_sub_f32_e32 v8, v13, v52
	s_waitcnt lgkmcnt(1)
	v_mfma_f32_32x32x16_bf16 v[32:47], v[0:3], v[92:95], 0
	v_exp_f32_e32 v188, v8
	ds_read_b128 v[8:11], v197 offset:33856
	v_sub_f32_e32 v48, 0xf149f2ca, v52
	v_exp_f32_e32 v1, v48
	ds_read_b128 v[48:51], v197 offset:33888
	v_sub_f32_e32 v0, v14, v52
	v_exp_f32_e32 v190, v0
	s_waitcnt lgkmcnt(2)
	v_mfma_f32_32x32x16_bf16 v[32:47], v[4:7], v[88:91], v[32:47]
	v_sub_f32_e32 v0, v15, v52
	v_exp_f32_e32 v156, v0
	v_mul_f32_e32 v0, 0, v1
	v_mov_b32_e32 v1, v0
	v_mov_b32_e32 v2, v0
	v_mov_b32_e32 v3, v0
	v_mov_b32_e32 v4, v0
	s_waitcnt lgkmcnt(1)
	v_mfma_f32_32x32x16_bf16 v[32:47], v[8:11], v[84:87], v[32:47]
	v_mov_b32_e32 v5, v0
	v_mov_b32_e32 v6, v0
	v_mov_b32_e32 v7, v0
	v_mov_b32_e32 v8, v0
	v_mov_b32_e32 v9, v0
	v_mov_b32_e32 v10, v0
	v_mov_b32_e32 v11, v0
	s_waitcnt lgkmcnt(0)
	v_mfma_f32_32x32x16_bf16 v[32:47], v[48:51], v[96:99], v[32:47]
	v_max_f32_e32 v48, v18, v18
	v_mov_b32_e32 v12, v0
	v_cvt_pk_bf16_f32 v200, v192, v198
	v_cvt_pk_bf16_f32 v201, v144, v142
	v_cvt_pk_bf16_f32 v202, v136, v146
	v_cvt_pk_bf16_f32 v203, v150, v152
	s_nop 5
	s_nop 1
	v_max_f32_e32 v13, v32, v33
	s_nop 1
	v_max_f32_e32 v14, v34, v35
	v_max3_f32 v13, v13, s23, v14
	s_nop 1
	v_max_f32_e32 v14, v16, v17
	v_max_f32_e32 v15, v19, v19
	v_max_f32_e32 v15, v48, v15
	v_max3_f32 v13, v13, v14, v15
	s_nop 1
	v_max_f32_e32 v14, v36, v37
	s_nop 1
	v_max_f32_e32 v15, v38, v39
	v_max3_f32 v13, v13, v14, v15
	s_nop 1
	v_max_f32_e32 v14, v20, v21
	s_nop 1
	v_max_f32_e32 v15, v22, v23
	v_max3_f32 v13, v13, v14, v15
	s_nop 1
	v_max_f32_e32 v14, v40, v41
	s_nop 1
	v_max_f32_e32 v15, v42, v43
	v_max3_f32 v13, v13, v14, v15
	s_nop 1
	v_max_f32_e32 v14, v24, v25
	s_nop 1
	v_max_f32_e32 v15, v26, v27
	v_max3_f32 v13, v13, v14, v15
	s_nop 1
	v_max_f32_e32 v14, v44, v45
	s_nop 1
	v_max_f32_e32 v15, v46, v47
	v_max3_f32 v13, v13, v14, v15
	s_nop 1
	v_max_f32_e32 v14, v28, v29
	s_nop 1
	v_max_f32_e32 v15, v30, v31
	v_max3_f32 v48, v13, v14, v15
	ds_bpermute_b32 v49, v210, v48
	v_mov_b32_e32 v13, v0
	v_mov_b32_e32 v14, v0
	v_mov_b32_e32 v15, v0
	s_waitcnt lgkmcnt(0)
	v_max3_f32 v199, v52, v48, v49
	v_sub_f32_e32 v16, v16, v199
	v_exp_f32_e32 v83, v16
	v_sub_f32_e32 v16, v17, v199
	v_exp_f32_e32 v135, v16
	v_sub_f32_e32 v16, v18, v199
	v_exp_f32_e32 v137, v16
	v_sub_f32_e32 v16, v19, v199
	v_exp_f32_e32 v147, v16
	v_sub_f32_e32 v16, v36, v199
	v_exp_f32_e32 v151, v16
	v_sub_f32_e32 v16, v37, v199
	v_exp_f32_e32 v153, v16
	v_sub_f32_e32 v16, v38, v199
	v_exp_f32_e32 v149, v16
	v_sub_f32_e32 v16, v39, v199
	v_exp_f32_e32 v155, v16
	v_sub_f32_e32 v16, v20, v199
	v_exp_f32_e32 v159, v16
	v_sub_f32_e32 v16, v21, v199
	v_sub_f32_e32 v48, v52, v199
	v_mfma_f32_32x32x16_bf16 v[50:65], v[128:131], v[200:203], v[0:15]
	v_exp_f32_e32 v161, v16
	v_mov_b64_e32 v[16:17], v[14:15]
	v_sub_f32_e32 v18, v22, v199
	v_exp_f32_e32 v163, v18
	v_cvt_pk_bf16_f32 v18, v162, v168
	s_nop 1
	v_mov_b64_e32 v[14:15], v[12:13]
	v_mov_b64_e32 v[12:13], v[10:11]
	v_mov_b64_e32 v[10:11], v[8:9]
	v_mov_b64_e32 v[8:9], v[6:7]
	v_mov_b64_e32 v[6:7], v[4:5]
	v_mov_b64_e32 v[4:5], v[2:3]
	v_mov_b64_e32 v[2:3], v[0:1]
	v_cvt_pk_bf16_f32 v19, v164, v166
	v_cvt_pk_bf16_f32 v20, v176, v178
	v_mfma_f32_32x32x16_bf16 v[2:17], v[124:127], v[200:203], v[2:17]
	v_cvt_pk_bf16_f32 v21, v182, v184
	v_sub_f32_e32 v1, v23, v199
	v_exp_f32_e32 v169, v1
	v_sub_f32_e32 v1, v40, v199
	v_cvt_pk_bf16_f32 v22, v186, v188
	v_cvt_pk_bf16_f32 v23, v190, v156
	v_sub_f32_e32 v32, v32, v199
	v_mfma_f32_32x32x16_bf16 v[50:65], v[120:123], v[18:21], v[50:65]
	v_exp_f32_e32 v165, v1
	v_sub_f32_e32 v1, v41, v199
	v_exp_f32_e32 v145, v32
	v_sub_f32_e32 v32, v33, v199
	v_exp_f32_e32 v167, v1
	v_sub_f32_e32 v1, v42, v199
	v_exp_f32_e32 v143, v32
	v_mfma_f32_32x32x16_bf16 v[2:17], v[116:119], v[18:21], v[2:17]
	v_cvt_pk_bf16_f32 v18, v140, v138
	v_cvt_pk_bf16_f32 v19, v82, v134
	v_cvt_pk_bf16_f32 v20, v148, v154
	v_cvt_pk_bf16_f32 v21, v158, v160
	v_sub_f32_e32 v32, v34, v199
	v_exp_f32_e32 v171, v1
	v_sub_f32_e32 v1, v43, v199
	v_mfma_f32_32x32x16_bf16 v[50:65], v[112:115], v[18:21], v[50:65]
	v_exp_f32_e32 v141, v32
	v_sub_f32_e32 v32, v35, v199
	v_exp_f32_e32 v173, v1
	v_sub_f32_e32 v1, v24, v199
	v_exp_f32_e32 v139, v32
	v_exp_f32_e32 v175, v1
	v_sub_f32_e32 v1, v25, v199
	v_mfma_f32_32x32x16_bf16 v[2:17], v[108:111], v[18:21], v[2:17]
	v_cvt_pk_bf16_f32 v20, v170, v172
	v_cvt_pk_bf16_f32 v21, v174, v180
	v_exp_f32_e32 v18, v48
	v_exp_f32_e32 v181, v1
	v_sub_f32_e32 v1, v44, v199
	v_exp_f32_e32 v183, v1
	v_sub_f32_e32 v1, v45, v199
	v_mfma_f32_32x32x16_bf16 v[50:65], v[78:81], v[20:23], v[50:65]
	ds_read_b64_tr_b16 v[78:79], v211 offset:43008
	ds_read_b64_tr_b16 v[80:81], v211 offset:44160
	ds_read_b64_tr_b16 v[110:111], v211 offset:44224
	ds_read_b64_tr_b16 v[108:109], v211 offset:43072
	ds_read_b64_tr_b16 v[112:113], v211 offset:45312
	ds_read_b64_tr_b16 v[114:115], v211 offset:46464
	v_exp_f32_e32 v185, v1
	v_sub_f32_e32 v1, v46, v199
	v_exp_f32_e32 v187, v1
	v_sub_f32_e32 v1, v47, v199
	v_cvt_pk_bf16_f32 v116, v145, v143
	v_cvt_pk_bf16_f32 v117, v141, v139
	v_mfma_f32_32x32x16_bf16 v[2:17], v[74:77], v[20:23], v[2:17]
	v_cvt_pk_bf16_f32 v118, v151, v153
	v_cvt_pk_bf16_f32 v119, v149, v155
	v_mul_f32_e64 v48, v64, v18
	v_mul_f32_e64 v49, v65, v18
	v_mul_f32_e64 v46, v62, v18
	v_mul_f32_e64 v47, v63, v18
	v_pk_mul_f32 v[44:45], v[60:61], v[18:19] op_sel_hi:[1,0]
	v_pk_mul_f32 v[42:43], v[58:59], v[18:19] op_sel_hi:[1,0]
	v_pk_mul_f32 v[40:41], v[56:57], v[18:19] op_sel_hi:[1,0]
	v_pk_mul_f32 v[38:39], v[54:55], v[18:19] op_sel_hi:[1,0]
	v_pk_mul_f32 v[36:37], v[52:53], v[18:19] op_sel_hi:[1,0]
	v_pk_mul_f32 v[34:35], v[50:51], v[18:19] op_sel_hi:[1,0]
	v_pk_mul_f32 v[16:17], v[16:17], v[18:19] op_sel_hi:[1,0]
	v_pk_mul_f32 v[14:15], v[14:15], v[18:19] op_sel_hi:[1,0]
	v_pk_mul_f32 v[12:13], v[12:13], v[18:19] op_sel_hi:[1,0]
	v_pk_mul_f32 v[10:11], v[10:11], v[18:19] op_sel_hi:[1,0]
	v_pk_mul_f32 v[8:9], v[8:9], v[18:19] op_sel_hi:[1,0]
	v_pk_mul_f32 v[6:7], v[6:7], v[18:19] op_sel_hi:[1,0]
	v_pk_mul_f32 v[4:5], v[4:5], v[18:19] op_sel_hi:[1,0]
	v_pk_mul_f32 v[2:3], v[2:3], v[18:19] op_sel_hi:[1,0]
	s_waitcnt lgkmcnt(4)
	v_mfma_f32_32x32x16_bf16 v[34:49], v[78:81], v[116:119], v[34:49]
	v_exp_f32_e32 v189, v1
	ds_read_b64_tr_b16 v[22:23], v211 offset:46528
	ds_read_b64_tr_b16 v[20:21], v211 offset:45376
	v_cvt_pk_bf16_f32 v50, v165, v167
	v_cvt_pk_bf16_f32 v51, v171, v173
	v_cvt_pk_bf16_f32 v52, v183, v185
	v_cvt_pk_bf16_f32 v53, v187, v189
	v_sub_f32_e32 v1, v26, v199
	s_waitcnt lgkmcnt(4)
	v_mfma_f32_32x32x16_bf16 v[2:17], v[108:111], v[116:119], v[2:17]
	v_exp_f32_e32 v177, v1
	v_sub_f32_e32 v1, v27, v199
	ds_read_b64_tr_b16 v[24:25], v211 offset:47616
	ds_read_b64_tr_b16 v[26:27], v211 offset:48768
	v_exp_f32_e32 v179, v1
	v_sub_f32_e32 v1, v28, v199
	v_exp_f32_e32 v191, v1
	v_sub_f32_e32 v1, v29, v199
	s_waitcnt lgkmcnt(4)
	v_mfma_f32_32x32x16_bf16 v[34:49], v[112:115], v[50:53], v[34:49]
	v_exp_f32_e32 v157, v1
	v_sub_f32_e32 v1, v30, v199
	v_sub_f32_e32 v19, v31, v199
	v_exp_f32_e32 v1, v1
	v_exp_f32_e32 v19, v19
	v_cvt_pk_bf16_f32 v28, v175, v181
	v_cvt_pk_bf16_f32 v29, v177, v179
	s_waitcnt lgkmcnt(2)
	v_mfma_f32_32x32x16_bf16 v[2:17], v[20:23], v[50:53], v[2:17]
	ds_read_b64_tr_b16 v[22:23], v211 offset:48832
	ds_read_b64_tr_b16 v[20:21], v211 offset:47680
	v_cvt_pk_bf16_f32 v50, v83, v135
	v_cvt_pk_bf16_f32 v51, v137, v147
	v_cvt_pk_bf16_f32 v52, v159, v161
	v_cvt_pk_bf16_f32 v53, v163, v169
	v_cvt_pk_bf16_f32 v30, v191, v157
	v_cvt_pk_bf16_f32 v31, v1, v19
	s_waitcnt lgkmcnt(2)
	v_mfma_f32_32x32x16_bf16 v[34:49], v[24:27], v[50:53], v[34:49]
	ds_read_b64_tr_b16 v[24:25], v211 offset:49920
	ds_read_b64_tr_b16 v[26:27], v211 offset:51072
	s_waitcnt lgkmcnt(2)
	v_mfma_f32_32x32x16_bf16 v[2:17], v[20:23], v[50:53], v[2:17]
	ds_read_b64_tr_b16 v[22:23], v211 offset:51136
	ds_read_b64_tr_b16 v[20:21], v211 offset:49984
	s_waitcnt vmcnt(3)
	ds_write_b128 v207, v[66:69] offset:15360
	s_waitcnt vmcnt(2)
	ds_write_b128 v207, v[70:73] offset:24576
	s_waitcnt lgkmcnt(0)
	s_barrier
	v_mfma_f32_32x32x16_bf16 v[34:49], v[24:27], v[28:31], v[34:49]
	v_mfma_f32_32x32x16_bf16 v[2:17], v[20:23], v[28:31], v[2:17]
	ds_read_b128 v[20:23], v196 offset:15360
	ds_read_b128 v[24:27], v196 offset:15392
	s_waitcnt lgkmcnt(1)
	v_mfma_f32_32x32x16_bf16 v[52:67], v[20:23], v[92:95], 0
	s_waitcnt lgkmcnt(0)
	v_mfma_f32_32x32x16_bf16 v[52:67], v[24:27], v[88:91], v[52:67]
	ds_read_b128 v[20:23], v196 offset:15424
	ds_read_b128 v[24:27], v196 offset:15456
	s_waitcnt lgkmcnt(1)
	v_mfma_f32_32x32x16_bf16 v[52:67], v[20:23], v[84:87], v[52:67]
	v_add_f32_e32 v20, 0, v192
	v_add_f32_e32 v192, v198, v20
	v_add_f32_e64 v20, v144, v192
	v_add_f32_e64 v21, v145, v193
	v_add_f32_e64 v20, v142, v20
	v_add_f32_e64 v21, v143, v21
	v_pk_add_f32 v[20:21], v[140:141], v[20:21]
	s_waitcnt lgkmcnt(0)
	v_mfma_f32_32x32x16_bf16 v[52:67], v[24:27], v[96:99], v[52:67]
	v_add_f32_e64 v28, v138, v20
	v_add_f32_e64 v29, v139, v21
	ds_read_b128 v[20:23], v197 offset:15360
	v_add_f32_e64 v24, v82, v28
	v_add_f32_e64 v25, v83, v29
	v_pk_add_f32 v[24:25], v[134:135], v[24:25]
	s_nop 0
	v_pk_add_f32 v[24:25], v[136:137], v[24:25]
	s_nop 0
	v_pk_add_f32 v[24:25], v[146:147], v[24:25]
	s_nop 0
	v_pk_add_f32 v[24:25], v[150:151], v[24:25]
	s_nop 0
	v_pk_add_f32 v[28:29], v[152:153], v[24:25]
	ds_read_b128 v[24:27], v197 offset:15392
	s_waitcnt lgkmcnt(1)
	v_mfma_f32_32x32x16_bf16 v[68:83], v[20:23], v[92:95], 0
	v_add_f32_e64 v20, v148, v28
	v_add_f32_e64 v21, v149, v29
	v_add_f32_e64 v20, v154, v20
	v_add_f32_e64 v21, v155, v21
	v_add_f32_e64 v20, v158, v20
	v_add_f32_e64 v21, v159, v21
	v_pk_add_f32 v[20:21], v[160:161], v[20:21]
	s_waitcnt lgkmcnt(0)
	v_mfma_f32_32x32x16_bf16 v[68:83], v[24:27], v[88:91], v[68:83]
	v_add_f32_e64 v20, v162, v20
	v_add_f32_e64 v21, v163, v21
	v_add_f32_e64 v28, v168, v20
	v_add_f32_e64 v29, v169, v21
	ds_read_b128 v[20:23], v197 offset:15424
	v_pk_add_f32 v[24:25], v[164:165], v[28:29]
	s_nop 0
	v_pk_add_f32 v[24:25], v[166:167], v[24:25]
	s_nop 0
	v_pk_add_f32 v[24:25], v[170:171], v[24:25]
	s_nop 0
	v_pk_add_f32 v[24:25], v[172:173], v[24:25]
	s_nop 0
	v_pk_add_f32 v[24:25], v[174:175], v[24:25]
	s_nop 0
	v_pk_add_f32 v[28:29], v[180:181], v[24:25]
	ds_read_b128 v[24:27], v197 offset:15456
	s_waitcnt lgkmcnt(1)
	v_mfma_f32_32x32x16_bf16 v[68:83], v[20:23], v[84:87], v[68:83]
	v_add_f32_e64 v20, v176, v28
	v_add_f32_e64 v21, v177, v29
	v_add_f32_e64 v20, v178, v20
	v_add_f32_e64 v21, v179, v21
	v_add_f32_e64 v20, v182, v20
	v_add_f32_e64 v21, v183, v21
	v_pk_add_f32 v[20:21], v[184:185], v[20:21]
	s_waitcnt lgkmcnt(0)
	v_mfma_f32_32x32x16_bf16 v[68:83], v[24:27], v[96:99], v[68:83]
	v_max_f32_e32 v25, v54, v54
	v_add_f32_e64 v20, v186, v20
	v_add_f32_e64 v21, v187, v21
	v_add_f32_e64 v20, v188, v20
	v_add_f32_e64 v21, v189, v21
	v_pk_add_f32 v[20:21], v[190:191], v[20:21]
	s_nop 5
	s_nop 1
	v_max_f32_e32 v22, v68, v69
	s_nop 1
	v_max_f32_e32 v23, v70, v71
	v_max3_f32 v22, v22, s23, v23
	s_nop 1
	v_max_f32_e32 v23, v52, v53
	v_max_f32_e32 v24, v55, v55
	v_max_f32_e32 v24, v25, v24
	v_max3_f32 v22, v22, v23, v24
	s_nop 1
	v_max_f32_e32 v23, v72, v73
	s_nop 1
	v_max_f32_e32 v24, v74, v75
	v_max3_f32 v22, v22, v23, v24
	s_nop 1
	v_max_f32_e32 v23, v56, v57
	s_nop 1
	v_max_f32_e32 v24, v58, v59
	v_max3_f32 v22, v22, v23, v24
	s_nop 1
	v_max_f32_e32 v23, v76, v77
	s_nop 1
	v_max_f32_e32 v24, v78, v79
	v_max3_f32 v22, v22, v23, v24
	s_nop 1
	v_max_f32_e32 v23, v60, v61
	s_nop 1
	v_max_f32_e32 v24, v62, v63
	v_max3_f32 v22, v22, v23, v24
	s_nop 1
	v_max_f32_e32 v23, v80, v81
	s_nop 1
	v_max_f32_e32 v24, v82, v83
	v_max3_f32 v22, v22, v23, v24
	s_nop 1
	v_max_f32_e32 v23, v64, v65
	s_nop 1
	v_max_f32_e32 v24, v66, v67
	v_max3_f32 v22, v22, v23, v24
	ds_bpermute_b32 v23, v210, v22
	v_pk_add_f32 v[20:21], v[156:157], v[20:21]
	s_waitcnt lgkmcnt(0)
	v_max3_f32 v125, v199, v22, v23
	v_pk_add_f32 v[0:1], v[0:1], v[20:21]
	v_sub_f32_e32 v22, v58, v125
	v_add_f32_e32 v1, v1, v19
	v_sub_f32_e32 v19, v68, v125
	v_fmac_f32_e32 v1, v0, v18
	v_sub_f32_e32 v18, v55, v125
	v_exp_f32_e32 v127, v19
	v_sub_f32_e32 v19, v69, v125
	v_exp_f32_e32 v124, v18
	v_sub_f32_e32 v18, v72, v125
	v_exp_f32_e32 v129, v19
	v_exp_f32_e32 v126, v18
	v_sub_f32_e32 v18, v73, v125
	v_exp_f32_e32 v128, v18
	v_sub_f32_e32 v18, v74, v125
	v_exp_f32_e32 v144, v18
	v_sub_f32_e32 v18, v75, v125
	v_add_f32_e32 v0, 0, v127
	v_exp_f32_e32 v146, v18
	v_sub_f32_e32 v18, v56, v125
	v_add_f32_e32 v192, v129, v0
	v_sub_f32_e32 v0, v70, v125
	v_exp_f32_e32 v130, v18
	v_sub_f32_e32 v18, v57, v125
	v_exp_f32_e32 v136, v0
	v_sub_f32_e32 v0, v71, v125
	v_exp_f32_e32 v134, v18
	ds_read_b64_tr_b16 v[164:165], v211 offset:24576
	ds_read_b64_tr_b16 v[166:167], v211 offset:25728
	ds_read_b64_tr_b16 v[170:171], v211 offset:25792
	ds_read_b64_tr_b16 v[168:169], v211 offset:24640
	ds_read_b64_tr_b16 v[120:121], v211 offset:26880
	ds_read_b64_tr_b16 v[122:123], v211 offset:28032
	ds_read_b64_tr_b16 v[114:115], v211 offset:28096
	ds_read_b64_tr_b16 v[112:113], v211 offset:26944
	ds_read_b64_tr_b16 v[116:117], v211 offset:29184
	ds_read_b64_tr_b16 v[118:119], v211 offset:30336
	ds_read_b64_tr_b16 v[110:111], v211 offset:30400
	ds_read_b64_tr_b16 v[108:109], v211 offset:29248
	ds_read_b64_tr_b16 v[72:73], v211 offset:31488
	ds_read_b64_tr_b16 v[74:75], v211 offset:32640
	ds_read_b64_tr_b16 v[70:71], v211 offset:32704
	ds_read_b64_tr_b16 v[68:69], v211 offset:31552
	s_waitcnt vmcnt(1)
	ds_write_b128 v207, v[100:103] offset:33792
	s_waitcnt vmcnt(0)
	ds_write_b128 v207, v[104:107] offset:43008
	s_waitcnt lgkmcnt(0)
	s_barrier
	ds_read_b128 v[18:21], v196 offset:33792
	v_exp_f32_e32 v100, v22
	v_sub_f32_e32 v22, v59, v125
	v_exp_f32_e32 v138, v0
	v_sub_f32_e32 v0, v52, v125
	v_exp_f32_e32 v102, v22
	v_sub_f32_e32 v22, v76, v125
	v_exp_f32_e32 v140, v0
	v_sub_f32_e32 v0, v53, v125
	v_exp_f32_e32 v76, v22
	v_sub_f32_e32 v22, v77, v125
	ds_read_b128 v[50:53], v196 offset:33824
	v_exp_f32_e32 v104, v22
	s_waitcnt lgkmcnt(1)
	v_mfma_f32_32x32x16_bf16 v[18:33], v[18:21], v[92:95], 0
	v_exp_f32_e32 v142, v0
	v_sub_f32_e32 v0, v54, v125
	v_sub_f32_e32 v54, v78, v125
	v_exp_f32_e32 v150, v54
	v_sub_f32_e32 v54, v79, v125
	v_exp_f32_e32 v154, v54
	v_sub_f32_e32 v54, v60, v125
	v_exp_f32_e32 v158, v54
	ds_read_b128 v[54:57], v196 offset:33856
	s_waitcnt lgkmcnt(1)
	v_mfma_f32_32x32x16_bf16 v[18:33], v[50:53], v[88:91], v[18:33]
	v_sub_f32_e32 v50, v61, v125
	v_exp_f32_e32 v162, v50
	v_sub_f32_e32 v50, v62, v125
	v_exp_f32_e32 v78, v50
	v_sub_f32_e32 v50, v63, v125
	v_exp_f32_e32 v106, v50
	ds_read_b128 v[50:53], v196 offset:33888
	s_waitcnt lgkmcnt(1)
	v_mfma_f32_32x32x16_bf16 v[18:33], v[54:57], v[84:87], v[18:33]
	v_sub_f32_e32 v54, v80, v125
	v_exp_f32_e32 v80, v54
	v_sub_f32_e32 v54, v81, v125
	v_exp_f32_e32 v148, v54
	v_sub_f32_e32 v54, v82, v125
	v_exp_f32_e32 v82, v54
	ds_read_b128 v[54:57], v197 offset:33792
	ds_read_b128 v[172:175], v197 offset:33824
	s_waitcnt lgkmcnt(2)
	v_mfma_f32_32x32x16_bf16 v[18:33], v[50:53], v[96:99], v[18:33]
	v_sub_f32_e32 v50, v83, v125
	v_exp_f32_e32 v152, v50
	v_sub_f32_e32 v50, v64, v125
	v_exp_f32_e32 v156, v50
	v_sub_f32_e32 v50, v65, v125
	v_exp_f32_e32 v160, v50
	ds_read_b128 v[176:179], v197 offset:33856
	s_waitcnt lgkmcnt(2)
	v_mfma_f32_32x32x16_bf16 v[50:65], v[54:57], v[92:95], 0
	v_sub_f32_e32 v131, v199, v125
	v_exp_f32_e32 v180, v131
	v_sub_f32_e32 v67, v67, v125
	v_exp_f32_e32 v94, v67
	v_max_f32_e32 v79, v20, v20
	v_mul_f32_e32 v92, v1, v180
	v_pk_mul_f32 v[48:49], v[48:49], v[180:181] op_sel_hi:[1,0]
	s_waitcnt lgkmcnt(1)
	v_mfma_f32_32x32x16_bf16 v[50:65], v[172:175], v[88:91], v[50:65]
	ds_read_b128 v[88:91], v197 offset:33888
	v_mul_f32_e64 v46, v46, v180
	v_mul_f32_e64 v47, v47, v180
	v_mul_f32_e64 v44, v44, v180
	v_mul_f32_e64 v45, v45, v180
	v_pk_mul_f32 v[42:43], v[42:43], v[180:181] op_sel_hi:[1,0]
	v_pk_mul_f32 v[40:41], v[40:41], v[180:181] op_sel_hi:[1,0]
	v_pk_mul_f32 v[38:39], v[38:39], v[180:181] op_sel_hi:[1,0]
	v_pk_mul_f32 v[36:37], v[36:37], v[180:181] op_sel_hi:[1,0]
	s_waitcnt lgkmcnt(1)
	v_mfma_f32_32x32x16_bf16 v[50:65], v[176:179], v[84:87], v[50:65]
	v_mul_f32_e64 v34, v34, v180
	v_mul_f32_e64 v35, v35, v180
	v_mul_f32_e64 v16, v16, v180
	v_mul_f32_e64 v17, v17, v180
	v_mul_f32_e64 v14, v14, v180
	v_mul_f32_e64 v15, v15, v180
	v_pk_mul_f32 v[12:13], v[12:13], v[180:181] op_sel_hi:[1,0]
	v_pk_mul_f32 v[10:11], v[10:11], v[180:181] op_sel_hi:[1,0]
	v_pk_mul_f32 v[8:9], v[8:9], v[180:181] op_sel_hi:[1,0]
	v_pk_mul_f32 v[6:7], v[6:7], v[180:181] op_sel_hi:[1,0]
	s_waitcnt lgkmcnt(0)
	v_mfma_f32_32x32x16_bf16 v[50:65], v[88:91], v[96:99], v[50:65]
	v_mul_f32_e64 v4, v4, v180
	v_mul_f32_e64 v5, v5, v180
	v_mul_f32_e64 v2, v2, v180
	v_mul_f32_e64 v3, v3, v180
	v_cvt_pk_bf16_f32 v84, v127, v129
	v_cvt_pk_bf16_f32 v85, v136, v138
	v_cvt_pk_bf16_f32 v86, v126, v128
	v_cvt_pk_bf16_f32 v87, v144, v146
	v_sub_f32_e32 v66, v66, v125
	s_nop 2
	s_nop 1
	v_max_f32_e32 v1, v50, v51
	s_nop 1
	v_max_f32_e32 v67, v52, v53
	v_max3_f32 v1, v1, s23, v67
	s_nop 1
	v_max_f32_e32 v67, v18, v19
	v_max_f32_e32 v77, v21, v21
	v_max_f32_e32 v77, v79, v77
	v_max3_f32 v1, v1, v67, v77
	s_nop 1
	v_max_f32_e32 v67, v54, v55
	s_nop 1
	v_max_f32_e32 v77, v56, v57
	v_max3_f32 v1, v1, v67, v77
	s_nop 1
	v_max_f32_e32 v67, v22, v23
	s_nop 1
	v_max_f32_e32 v77, v24, v25
	v_max3_f32 v1, v1, v67, v77
	s_nop 1
	v_max_f32_e32 v67, v58, v59
	s_nop 1
	v_max_f32_e32 v77, v60, v61
	v_max3_f32 v1, v1, v67, v77
	s_nop 1
	v_max_f32_e32 v67, v26, v27
	s_nop 1
	v_max_f32_e32 v77, v28, v29
	v_max3_f32 v1, v1, v67, v77
	s_nop 1
	v_max_f32_e32 v67, v62, v63
	s_nop 1
	v_max_f32_e32 v77, v64, v65
	v_max3_f32 v1, v1, v67, v77
	s_nop 1
	v_max_f32_e32 v67, v30, v31
	s_nop 1
	v_max_f32_e32 v77, v32, v33
	v_max3_f32 v1, v1, v67, v77
	ds_bpermute_b32 v67, v210, v1
	v_mfma_f32_32x32x16_bf16 v[34:49], v[164:167], v[84:87], v[34:49]
	v_exp_f32_e32 v0, v0
	v_exp_f32_e32 v66, v66
	s_waitcnt lgkmcnt(0)
	v_max3_f32 v96, v125, v1, v67
	v_sub_f32_e32 v1, v50, v96
	v_exp_f32_e32 v137, v1
	v_sub_f32_e32 v1, v51, v96
	v_mfma_f32_32x32x16_bf16 v[2:17], v[168:171], v[84:87], v[2:17]
	v_exp_f32_e32 v139, v1
	v_sub_f32_e32 v1, v52, v96
	v_exp_f32_e32 v141, v1
	v_sub_f32_e32 v1, v53, v96
	v_exp_f32_e32 v143, v1
	v_sub_f32_e32 v1, v18, v96
	v_sub_f32_e32 v18, v19, v96
	v_sub_f32_e32 v67, v125, v96
	v_exp_f32_e32 v125, v18
	v_sub_f32_e32 v18, v20, v96
	v_exp_f32_e32 v127, v18
	v_sub_f32_e32 v18, v21, v96
	v_exp_f32_e32 v129, v18
	v_sub_f32_e32 v18, v54, v96
	v_exp_f32_e32 v1, v1
	v_exp_f32_e32 v145, v18
	v_pk_add_f32 v[18:19], v[136:137], v[192:193]
	v_cvt_pk_bf16_f32 v50, v76, v104
	v_cvt_pk_bf16_f32 v51, v150, v154
	v_cvt_pk_bf16_f32 v52, v80, v148
	v_cvt_pk_bf16_f32 v53, v82, v152
	v_pk_add_f32 v[18:19], v[138:139], v[18:19]
	v_cvt_pk_bf16_f32 v21, v0, v124
	v_mfma_f32_32x32x16_bf16 v[34:49], v[120:123], v[50:53], v[34:49]
	v_add_f32_e64 v18, v140, v18
	v_add_f32_e64 v19, v141, v19
	v_cvt_pk_bf16_f32 v20, v140, v142
	v_add_f32_e64 v18, v142, v18
	v_add_f32_e64 v19, v143, v19
	v_lshlrev_b32_e32 v192, 1, v206
	v_pk_add_f32 v[18:19], v[0:1], v[18:19]
	v_sub_f32_e32 v0, v55, v96
	v_exp_f32_e32 v147, v0
	v_mfma_f32_32x32x16_bf16 v[2:17], v[112:115], v[50:53], v[2:17]
	v_sub_f32_e32 v0, v56, v96
	v_exp_f32_e32 v131, v0
	v_sub_f32_e32 v0, v57, v96
	v_exp_f32_e32 v135, v0
	v_sub_f32_e32 v0, v22, v96
	v_exp_f32_e32 v101, v0
	v_sub_f32_e32 v0, v23, v96
	v_cvt_pk_bf16_f32 v22, v130, v134
	v_cvt_pk_bf16_f32 v23, v100, v102
	v_exp_f32_e32 v103, v0
	v_sub_f32_e32 v0, v24, v96
	v_mfma_f32_32x32x16_bf16 v[34:49], v[116:119], v[20:23], v[34:49]
	v_exp_f32_e32 v77, v0
	v_sub_f32_e32 v0, v25, v96
	v_exp_f32_e32 v105, v0
	v_sub_f32_e32 v0, v58, v96
	v_exp_f32_e32 v151, v0
	v_sub_f32_e32 v0, v59, v96
	v_exp_f32_e32 v155, v0
	v_mfma_f32_32x32x16_bf16 v[2:17], v[108:111], v[20:23], v[2:17]
	v_sub_f32_e32 v0, v60, v96
	v_exp_f32_e32 v159, v0
	v_sub_f32_e32 v0, v61, v96
	v_exp_f32_e32 v163, v0
	v_sub_f32_e32 v0, v26, v96
	v_cvt_pk_bf16_f32 v24, v158, v162
	v_exp_f32_e32 v79, v0
	v_sub_f32_e32 v0, v27, v96
	v_cvt_pk_bf16_f32 v25, v78, v106
	v_cvt_pk_bf16_f32 v26, v156, v160
	v_cvt_pk_bf16_f32 v27, v66, v94
	v_exp_f32_e32 v107, v0
	v_sub_f32_e32 v0, v28, v96
	v_mfma_f32_32x32x16_bf16 v[34:49], v[72:75], v[24:27], v[34:49]
	v_exp_f32_e32 v81, v0
	v_sub_f32_e32 v0, v29, v96
	v_pk_add_f32 v[18:19], v[124:125], v[18:19]
	v_exp_f32_e32 v149, v0
	v_sub_f32_e32 v0, v62, v96
	v_pk_add_f32 v[18:19], v[126:127], v[18:19]
	v_exp_f32_e32 v83, v0
	v_mfma_f32_32x32x16_bf16 v[2:17], v[68:71], v[24:27], v[2:17]
	v_sub_f32_e32 v0, v63, v96
	v_sub_f32_e32 v20, v64, v96
	v_add_f32_e64 v18, v128, v18
	v_add_f32_e64 v19, v129, v19
	v_exp_f32_e32 v153, v0
	v_exp_f32_e32 v0, v67
	v_exp_f32_e32 v157, v20
	ds_read_b64_tr_b16 v[20:21], v211 offset:43008
	ds_read_b64_tr_b16 v[22:23], v211 offset:44160
	ds_read_b64_tr_b16 v[26:27], v211 offset:44224
	ds_read_b64_tr_b16 v[24:25], v211 offset:43072
	v_lshlrev_b64 v[28:29], 11, v[132:133]
	v_pk_add_f32 v[18:19], v[144:145], v[18:19]
	v_lshl_add_u64 v[28:29], s[0:1], 0, v[28:29]
	v_pk_add_f32 v[18:19], v[146:147], v[18:19]
	v_lshl_add_u64 v[28:29], v[28:29], 0, s[16:17]
	v_pk_add_f32 v[18:19], v[130:131], v[18:19]
	v_lshl_add_u64 v[28:29], v[28:29], 0, v[192:193]
	v_pk_add_f32 v[18:19], v[134:135], v[18:19]
	v_pk_mul_f32 v[48:49], v[48:49], v[0:1] op_sel_hi:[1,0]
	v_pk_mul_f32 v[46:47], v[46:47], v[0:1] op_sel_hi:[1,0]
	v_pk_mul_f32 v[44:45], v[44:45], v[0:1] op_sel_hi:[1,0]
	v_pk_mul_f32 v[42:43], v[42:43], v[0:1] op_sel_hi:[1,0]
	v_pk_mul_f32 v[40:41], v[40:41], v[0:1] op_sel_hi:[1,0]
	v_pk_mul_f32 v[38:39], v[38:39], v[0:1] op_sel_hi:[1,0]
	v_pk_mul_f32 v[36:37], v[36:37], v[0:1] op_sel_hi:[1,0]
	v_pk_mul_f32 v[34:35], v[34:35], v[0:1] op_sel_hi:[1,0]
	v_pk_mul_f32 v[16:17], v[16:17], v[0:1] op_sel_hi:[1,0]
	v_cvt_pk_bf16_f32 v50, v137, v139
	v_cvt_pk_bf16_f32 v51, v141, v143
	v_cvt_pk_bf16_f32 v52, v145, v147
	ds_read_b64_tr_b16 v[54:55], v211 offset:45312
	ds_read_b64_tr_b16 v[56:57], v211 offset:46464
	ds_read_b64_tr_b16 v[60:61], v211 offset:46528
	ds_read_b64_tr_b16 v[58:59], v211 offset:45376
	ds_read_b64_tr_b16 v[68:69], v211 offset:47616
	ds_read_b64_tr_b16 v[70:71], v211 offset:48768
	ds_read_b64_tr_b16 v[74:75], v211 offset:48832
	ds_read_b64_tr_b16 v[72:73], v211 offset:47680
	ds_read_b64_tr_b16 v[84:85], v211 offset:49920
	ds_read_b64_tr_b16 v[86:87], v211 offset:51072
	ds_read_b64_tr_b16 v[90:91], v211 offset:51136
	ds_read_b64_tr_b16 v[88:89], v211 offset:49984
	s_waitcnt lgkmcnt(0)
	s_barrier
	v_mov_b64_e32 v[62:63], v[238:239]
	v_cvt_pk_bf16_f32 v53, v131, v135
	v_pk_mul_f32 v[14:15], v[14:15], v[0:1] op_sel_hi:[1,0]
	v_pk_mul_f32 v[12:13], v[12:13], v[0:1] op_sel_hi:[1,0]
	v_pk_mul_f32 v[10:11], v[10:11], v[0:1] op_sel_hi:[1,0]
	v_pk_mul_f32 v[8:9], v[8:9], v[0:1] op_sel_hi:[1,0]
	v_pk_mul_f32 v[6:7], v[6:7], v[0:1] op_sel_hi:[1,0]
	v_pk_mul_f32 v[4:5], v[4:5], v[0:1] op_sel_hi:[1,0]
	v_pk_mul_f32 v[2:3], v[2:3], v[0:1] op_sel_hi:[1,0]
	v_pk_add_f32 v[18:19], v[100:101], v[18:19]
	v_mfma_f32_32x32x16_bf16 v[34:49], v[20:23], v[50:53], v[34:49]
	v_add_f32_e64 v18, v102, v18
	v_add_f32_e64 v19, v103, v19
	v_sub_f32_e32 v20, v65, v96
	v_add_f32_e64 v18, v76, v18
	v_add_f32_e64 v19, v77, v19
	v_exp_f32_e32 v161, v20
	v_pk_add_f32 v[18:19], v[104:105], v[18:19]
	v_cvt_pk_bf16_f32 v20, v151, v155
	v_pk_add_f32 v[18:19], v[150:151], v[18:19]
	v_mfma_f32_32x32x16_bf16 v[2:17], v[24:27], v[50:53], v[2:17]
	v_mov_b64_e32 v[24:25], v[240:241]
	v_add_f32_e64 v18, v154, v18
	v_add_f32_e64 v19, v155, v19
	v_sub_f32_e32 v26, v30, v96
	v_add_f32_e64 v18, v158, v18
	v_add_f32_e64 v19, v159, v19
	v_cvt_pk_bf16_f32 v21, v159, v163
	v_pk_add_f32 v[18:19], v[162:163], v[18:19]
	v_cvt_pk_bf16_f32 v22, v83, v153
	v_cvt_pk_bf16_f32 v23, v157, v161
	v_exp_f32_e32 v67, v26
	v_mov_b64_e32 v[26:27], v[242:243]
	v_mfma_f32_32x32x16_bf16 v[34:49], v[54:57], v[20:23], v[34:49]
	v_sub_f32_e32 v30, v31, v96
	v_exp_f32_e32 v95, v30
	v_sub_f32_e32 v30, v32, v96
	v_exp_f32_e32 v93, v30
	v_sub_f32_e32 v30, v33, v96
	v_exp_f32_e32 v50, v30
	v_mov_b64_e32 v[30:31], v[244:245]
	v_mfma_f32_32x32x16_bf16 v[2:17], v[58:61], v[20:23], v[2:17]
	v_add_f32_e64 v22, v78, v18
	v_add_f32_e64 v23, v79, v19
	v_cvt_pk_bf16_f32 v18, v1, v125
	v_add_f32_e64 v22, v106, v22
	v_add_f32_e64 v23, v107, v23
	v_cvt_pk_bf16_f32 v19, v127, v129
	v_pk_add_f32 v[22:23], v[80:81], v[22:23]
	v_cvt_pk_bf16_f32 v20, v101, v103
	v_pk_add_f32 v[22:23], v[148:149], v[22:23]
	v_cvt_pk_bf16_f32 v21, v77, v105
	v_pk_add_f32 v[22:23], v[82:83], v[22:23]
	v_mov_b64_e32 v[32:33], v[246:247]
	v_pk_add_f32 v[22:23], v[152:153], v[22:23]
	v_mfma_f32_32x32x16_bf16 v[34:49], v[68:71], v[18:21], v[34:49]
	v_add_f32_e64 v22, v156, v22
	v_add_f32_e64 v23, v157, v23
	s_mov_b32 s0, s16
	v_add_f32_e64 v22, v160, v22
	v_add_f32_e64 v23, v161, v23
	v_writelane_b32 v255, s0, 35
	s_nop 1
	v_writelane_b32 v255, s1, 36
	v_mfma_f32_32x32x16_bf16 v[2:17], v[72:75], v[18:21], v[2:17]
	v_add_f32_e64 v18, v66, v22
	v_add_f32_e64 v19, v67, v23
	v_cvt_pk_bf16_f32 v20, v67, v95
	v_add_f32_e64 v18, v94, v18
	v_add_f32_e64 v19, v95, v19
	v_cvt_pk_bf16_f32 v21, v93, v50
	v_pk_add_f32 v[22:23], v[92:93], v[18:19]
	v_cvt_pk_bf16_f32 v18, v79, v107
	v_add_f32_e32 v23, v23, v50
	v_fmac_f32_e32 v23, v22, v0
	v_mov_b64_e32 v[0:1], v[248:249]
	v_cvt_pk_bf16_f32 v19, v81, v149
	ds_bpermute_b32 v22, v210, v23
	s_waitcnt lgkmcnt(0)
	v_add_f32_e32 v22, v23, v22
	v_mfma_f32_32x32x16_bf16 v[34:49], v[84:87], v[18:21], v[34:49]
	v_div_scale_f32 v23, s[0:1], v22, v22, 1.0
	v_rcp_f32_e32 v50, v23
	s_nop 0
	v_fma_f32 v51, -v23, v50, 1.0
	v_mfma_f32_32x32x16_bf16 v[2:17], v[88:91], v[18:21], v[2:17]
	v_mov_b64_e32 v[18:19], v[224:225]
	v_mov_b64_e32 v[20:21], v[226:227]
	v_fmac_f32_e32 v50, v51, v50
	v_div_scale_f32 v51, vcc, 1.0, v22, 1.0
	v_mul_f32_e32 v52, v51, v50
	v_fma_f32 v53, -v23, v52, v51
	v_fmac_f32_e32 v52, v53, v50
	v_fma_f32 v23, -v23, v52, v51
	v_div_fmas_f32 v23, v23, v50, v52
	v_div_fixup_f32 v22, v23, v22, 1.0
	v_pk_mul_f32 v[34:35], v[34:35], v[22:23] op_sel_hi:[1,0]
	s_waitcnt vmcnt(7)
	v_lshlrev_b32_e32 v50, 16, v62
	v_and_b32_e32 v51, 0xffff0000, v62
	v_pk_mul_f32 v[34:35], v[34:35], v[50:51]
	v_pk_mul_f32 v[36:37], v[36:37], v[22:23] op_sel_hi:[1,0]
	v_lshlrev_b32_e32 v50, 16, v63
	v_and_b32_e32 v51, 0xffff0000, v63
	v_pk_mul_f32 v[36:37], v[36:37], v[50:51]
	v_cvt_pk_bf16_f32 v34, v34, v35
	v_cvt_pk_bf16_f32 v35, v36, v37
	global_store_dwordx2 v[28:29], v[34:35], off
	v_pk_mul_f32 v[34:35], v[38:39], v[22:23] op_sel_hi:[1,0]
	s_waitcnt vmcnt(7)
	v_lshlrev_b32_e32 v36, 16, v24
	v_and_b32_e32 v37, 0xffff0000, v24
	v_pk_mul_f32 v[34:35], v[34:35], v[36:37]
	v_lshlrev_b32_e32 v36, 16, v25
	v_cvt_pk_bf16_f32 v24, v34, v35
	v_pk_mul_f32 v[34:35], v[40:41], v[22:23] op_sel_hi:[1,0]
	v_and_b32_e32 v37, 0xffff0000, v25
	v_pk_mul_f32 v[34:35], v[34:35], v[36:37]
	v_pk_mul_f32 v[2:3], v[2:3], v[22:23] op_sel_hi:[1,0]
	v_cvt_pk_bf16_f32 v25, v34, v35
	global_store_dwordx2 v[28:29], v[24:25], off offset:16
	v_pk_mul_f32 v[24:25], v[42:43], v[22:23] op_sel_hi:[1,0]
	s_waitcnt vmcnt(7)
	v_lshlrev_b32_e32 v34, 16, v26
	v_and_b32_e32 v35, 0xffff0000, v26
	v_pk_mul_f32 v[24:25], v[24:25], v[34:35]
	v_pk_mul_f32 v[34:35], v[44:45], v[22:23] op_sel_hi:[1,0]
	v_lshlrev_b32_e32 v26, 16, v27
	v_and_b32_e32 v27, 0xffff0000, v27
	v_pk_mul_f32 v[26:27], v[34:35], v[26:27]
	v_cvt_pk_bf16_f32 v24, v24, v25
	v_cvt_pk_bf16_f32 v25, v26, v27
	global_store_dwordx2 v[28:29], v[24:25], off offset:32
	v_pk_mul_f32 v[24:25], v[46:47], v[22:23] op_sel_hi:[1,0]
	s_waitcnt vmcnt(7)
	v_lshlrev_b32_e32 v26, 16, v30
	v_and_b32_e32 v27, 0xffff0000, v30
	v_pk_mul_f32 v[24:25], v[24:25], v[26:27]
	v_pk_mul_f32 v[26:27], v[48:49], v[22:23] op_sel_hi:[1,0]
	v_lshlrev_b32_e32 v30, 16, v31
	v_and_b32_e32 v31, 0xffff0000, v31
	v_pk_mul_f32 v[26:27], v[26:27], v[30:31]
	v_cvt_pk_bf16_f32 v24, v24, v25
	v_cvt_pk_bf16_f32 v25, v26, v27
	global_store_dwordx2 v[28:29], v[24:25], off offset:48
	s_waitcnt vmcnt(7)
	v_lshlrev_b32_e32 v24, 16, v32
	v_and_b32_e32 v25, 0xffff0000, v32
	v_pk_mul_f32 v[2:3], v[2:3], v[24:25]
	v_pk_mul_f32 v[4:5], v[4:5], v[22:23] op_sel_hi:[1,0]
	v_lshlrev_b32_e32 v24, 16, v33
	v_and_b32_e32 v25, 0xffff0000, v33
	v_pk_mul_f32 v[4:5], v[4:5], v[24:25]
	v_cvt_pk_bf16_f32 v2, v2, v3
	v_cvt_pk_bf16_f32 v3, v4, v5
	global_store_dwordx2 v[28:29], v[2:3], off offset:64
	v_pk_mul_f32 v[2:3], v[6:7], v[22:23] op_sel_hi:[1,0]
	s_waitcnt vmcnt(7)
	v_lshlrev_b32_e32 v4, 16, v0
	v_and_b32_e32 v5, 0xffff0000, v0
	v_pk_mul_f32 v[2:3], v[2:3], v[4:5]
	v_lshlrev_b32_e32 v4, 16, v1
	v_cvt_pk_bf16_f32 v0, v2, v3
	v_pk_mul_f32 v[2:3], v[8:9], v[22:23] op_sel_hi:[1,0]
	v_and_b32_e32 v5, 0xffff0000, v1
	v_pk_mul_f32 v[2:3], v[2:3], v[4:5]
	s_waitcnt vmcnt(6)
	v_lshlrev_b32_e32 v4, 16, v19
	v_cvt_pk_bf16_f32 v1, v2, v3
	global_store_dwordx2 v[28:29], v[0:1], off offset:80
	v_pk_mul_f32 v[0:1], v[10:11], v[22:23] op_sel_hi:[1,0]
	v_lshlrev_b32_e32 v2, 16, v18
	v_and_b32_e32 v3, 0xffff0000, v18
	v_pk_mul_f32 v[0:1], v[0:1], v[2:3]
	v_pk_mul_f32 v[2:3], v[12:13], v[22:23] op_sel_hi:[1,0]
	v_and_b32_e32 v5, 0xffff0000, v19
	v_pk_mul_f32 v[2:3], v[2:3], v[4:5]
	v_cvt_pk_bf16_f32 v0, v0, v1
	v_cvt_pk_bf16_f32 v1, v2, v3
	global_store_dwordx2 v[28:29], v[0:1], off offset:96
	v_pk_mul_f32 v[0:1], v[14:15], v[22:23] op_sel_hi:[1,0]
	s_waitcnt vmcnt(7)
	v_lshlrev_b32_e32 v2, 16, v20
	v_and_b32_e32 v3, 0xffff0000, v20
	v_pk_mul_f32 v[0:1], v[0:1], v[2:3]
	v_pk_mul_f32 v[2:3], v[16:17], v[22:23] op_sel_hi:[1,0]
	v_lshlrev_b32_e32 v4, 16, v21
	v_and_b32_e32 v5, 0xffff0000, v21
	v_pk_mul_f32 v[2:3], v[2:3], v[4:5]
	v_cvt_pk_bf16_f32 v0, v0, v1
	v_cvt_pk_bf16_f32 v1, v2, v3
	global_store_dwordx2 v[28:29], v[0:1], off offset:112
